# NA attention: 32 rpb bias loads per local chunk issued together (one wait) instead of load-wait chains
# speedup vs baseline: 1.0014x; 1.0014x over previous
.LBB0_118:
	s_ashr_i32 s2, s63, 6
	s_ashr_i32 s56, s63, 2
	s_ashr_i32 s3, s2, 31
	s_and_b32 s58, s56, 15
	s_lshl_b64 s[2:3], s[2:3], 10
	s_add_u32 s2, s2, 0x2000
	s_addc_u32 s3, s3, 0
	s_lshl_b64 s[20:21], s[2:3], 11
	v_readlane_b32 s22, v253, 4
	v_readlane_b32 s23, v253, 5
	s_add_u32 s20, s22, s20
	s_addc_u32 s21, s23, s21
	s_lshl_b32 s26, s58, 7
	s_add_u32 s34, s20, s26
	s_addc_u32 s35, s21, 0
	s_lshl_b32 s20, s63, 2
	s_and_b32 s22, s20, 12
	v_sub_u32_e64 v0, s22, 4 clamp
	v_lshlrev_b32_e32 v1, 6, v0
	v_add_u32_e32 v2, v1, v108
	v_ashrrev_i32_e32 v3, 31, v2
	v_lshl_add_u64 v[70:71], s[34:35], 0, v[178:179]
	v_lshlrev_b64 v[2:3], 11, v[2:3]
	v_lshl_add_u64 v[2:3], v[70:71], 0, v[2:3]
	s_barrier
	global_load_dwordx4 v[12:15], v[2:3], off
	v_and_b32_e32 v1, 0x100, v1
	s_ashr_i32 s57, s56, 31
	v_add_u32_e32 v6, v1, v108
	s_movk_i32 s59, 0x90
	s_lshl_b64 s[36:37], s[56:57], 17
	v_mad_u64_u32 v[80:81], s[34:35], v6, s59, v[110:111]
	v_lshl_add_u64 v[68:69], v[138:139], 0, s[36:37]
	s_max_u32 s21, s22, 4
	s_lshl_b32 s20, s21, 6
	v_lshl_add_u32 v146, v1, 1, v109
	s_add_i32 s34, s20, 0xffffff40
	s_and_b32 s23, s34, 0x140
	s_mov_b32 s35, s27
	v_mov_b32_e32 v145, s3
	v_lshl_add_u64 v[142:143], v[112:113], 0, s[26:27]
	s_mov_b64 s[0:1], s[90:91]
	v_readlane_b32 s80, v253, 46
	v_readlane_b32 s94, v253, 60
	v_readlane_b32 s95, v253, 61
	v_lshlrev_b32_e32 v97, 2, v122
	v_lshlrev_b32_e32 v95, 2, v126
	v_lshlrev_b32_e32 v93, 2, v124
	v_lshlrev_b32_e32 v98, 2, v118
	v_lshlrev_b32_e32 v92, 2, v128
	v_lshlrev_b32_e32 v99, 2, v114
	v_lshlrev_b32_e32 v96, 2, v116
	v_lshlrev_b32_e32 v94, 2, v120
	v_readlane_b32 s81, v253, 47
	v_readlane_b32 s82, v253, 48
	v_readlane_b32 s83, v253, 49
	v_readlane_b32 s84, v253, 50
	v_readlane_b32 s85, v253, 51
	v_readlane_b32 s86, v253, 52
	v_readlane_b32 s87, v253, 53
	v_readlane_b32 s88, v253, 54
	v_readlane_b32 s89, v253, 55
	v_readlane_b32 s90, v253, 56
	v_readlane_b32 s91, v253, 57
	v_readlane_b32 s92, v253, 58
	v_readlane_b32 s93, v253, 59
	v_lshlrev_b32_e32 v2, 7, v0
	v_mov_b32_e32 v3, v179
	v_lshl_add_u64 v[2:3], v[68:69], 0, v[2:3]
	global_load_dwordx4 v[16:19], v[2:3], off
	v_add_u32_e32 v2, s34, v108
	v_ashrrev_i32_e32 v3, 31, v2
	v_lshlrev_b64 v[2:3], 11, v[2:3]
	v_lshl_add_u64 v[2:3], v[70:71], 0, v[2:3]
	global_load_dwordx4 v[20:23], v[2:3], off
	v_add_u32_e32 v1, s23, v108
	v_mad_u64_u32 v[82:83], s[36:37], v1, s59, v[110:111]
	v_lshl_add_u32 v147, s23, 1, v109
	v_lshl_add_u64 v[2:3], s[34:35], 1, v[68:69]
	global_load_dwordx4 v[24:27], v[2:3], off
	s_add_i32 s34, s20, 0xffffff80
	s_and_b32 s23, s34, 0x180
	v_add_u32_e32 v2, s34, v108
	v_ashrrev_i32_e32 v3, 31, v2
	v_lshlrev_b64 v[2:3], 11, v[2:3]
	v_lshl_add_u64 v[2:3], v[70:71], 0, v[2:3]
	global_load_dwordx4 v[28:31], v[2:3], off
	v_add_u32_e32 v1, s23, v108
	v_mad_u64_u32 v[84:85], s[36:37], v1, s59, v[110:111]
	v_lshl_add_u32 v148, s23, 1, v109
	v_lshl_add_u64 v[2:3], s[34:35], 1, v[68:69]
	global_load_dwordx4 v[32:35], v[2:3], off
	s_sub_i32 s34, s20, 64
	s_and_b32 s23, s34, 0x1c0
	v_add_u32_e32 v2, s34, v108
	v_ashrrev_i32_e32 v3, 31, v2
	v_lshlrev_b64 v[2:3], 11, v[2:3]
	v_lshl_add_u64 v[2:3], v[70:71], 0, v[2:3]
	global_load_dwordx4 v[36:39], v[2:3], off
	v_add_u32_e32 v1, s23, v108
	v_mad_u64_u32 v[86:87], s[36:37], v1, s59, v[110:111]
	v_lshl_add_u32 v149, s23, 1, v109
	s_and_b32 s23, s20, 0x100
	v_lshl_add_u64 v[2:3], s[34:35], 1, v[68:69]
	global_load_dwordx4 v[40:43], v[2:3], off
	v_add_u32_e32 v2, s20, v108
	v_ashrrev_i32_e32 v3, 31, v2
	v_lshlrev_b64 v[2:3], 11, v[2:3]
	v_lshl_add_u64 v[2:3], v[70:71], 0, v[2:3]
	global_load_dwordx4 v[44:47], v[2:3], off
	v_add_u32_e32 v1, s23, v108
	v_mad_u64_u32 v[100:101], s[34:35], v1, s59, v[110:111]
	s_lshl_b32 s34, s21, 7
	s_mov_b32 s35, s27
	v_lshl_add_u32 v150, s23, 1, v109
	s_or_b32 s21, s20, 64
	v_lshl_add_u64 v[6:7], v[68:69], 0, s[34:35]
	global_load_dwordx4 v[48:51], v[6:7], off
	v_add_u32_e32 v2, s21, v108
	v_ashrrev_i32_e32 v3, 31, v2
	v_lshlrev_b64 v[2:3], 11, v[2:3]
	v_lshl_add_u64 v[2:3], v[70:71], 0, v[2:3]
	global_load_dwordx4 v[52:55], v[2:3], off
	s_and_b32 s21, s21, 0x140
	v_add_u32_e32 v1, s21, v108
	v_mad_u64_u32 v[102:103], s[34:35], v1, s59, v[110:111]
	v_lshl_add_u32 v151, s21, 1, v109
	s_or_b32 s21, s20, 0x80
	s_or_b32 s20, s20, 0xc0
	global_load_dwordx4 v[56:59], v[6:7], off offset:128
	v_add_u32_e32 v2, s21, v108
	v_ashrrev_i32_e32 v3, 31, v2
	v_lshlrev_b64 v[2:3], 11, v[2:3]
	v_lshl_add_u64 v[2:3], v[70:71], 0, v[2:3]
	global_load_dwordx4 v[60:63], v[2:3], off
	s_and_b32 s21, s21, 0x180
	v_add_u32_e32 v1, s21, v108
	v_mad_u64_u32 v[104:105], s[34:35], v1, s59, v[110:111]
	v_lshl_add_u32 v152, s21, 1, v109
	global_load_dwordx4 v[64:67], v[6:7], off offset:256
	v_add_u32_e32 v2, s20, v108
	v_ashrrev_i32_e32 v3, 31, v2
	v_lshlrev_b64 v[2:3], 11, v[2:3]
	v_lshl_add_u64 v[2:3], v[70:71], 0, v[2:3]
	global_load_dwordx4 v[72:75], v[2:3], off
	s_and_b32 s20, s20, 0x1c0
	v_add_u32_e32 v1, s20, v108
	v_mad_u64_u32 v[106:107], s[34:35], v1, s59, v[110:111]
	v_lshl_add_u32 v153, s20, 1, v109
	s_mul_i32 s20, s58, 0x744
	s_add_u32 s36, s94, s20
	v_readfirstlane_b32 s20, v0
	s_addc_u32 s23, s95, 0
	s_add_i32 s20, s20, s61
	s_sub_i32 s21, s20, s22
	s_lshl_b32 s20, s20, 6
	s_and_b32 s35, s20, 0x100
	v_or_b32_e32 v0, s35, v115
	s_or_b32 s34, s35, 64
	s_or_b32 s33, s35, 0x80
	s_or_b32 s26, s35, 0xc0
	s_mul_i32 s20, s21, 31
	s_ashr_i32 s21, s20, 31
	s_lshl_b64 s[20:21], s[20:21], 2
	s_add_u32 s20, s36, s20
	s_addc_u32 s21, s23, s21
	global_load_dwordx4 v[76:79], v[6:7], off offset:384
	s_waitcnt vmcnt(15)
	ds_write_b128 v80, v[12:15]
	s_waitcnt vmcnt(14)
	ds_write_b128 v146, v[16:19]
	s_waitcnt vmcnt(13)
	ds_write_b128 v82, v[20:23]
	s_waitcnt vmcnt(12)
	ds_write_b128 v147, v[24:27]
	s_waitcnt vmcnt(11)
	ds_write_b128 v84, v[28:31]
	s_waitcnt vmcnt(10)
	ds_write_b128 v148, v[32:35]
	s_waitcnt vmcnt(9)
	ds_write_b128 v86, v[36:39]
	s_waitcnt vmcnt(8)
	ds_write_b128 v149, v[40:43]
	s_waitcnt vmcnt(7)
	ds_write_b128 v100, v[44:47]
	s_waitcnt vmcnt(6)
	ds_write_b128 v150, v[48:51]
	s_waitcnt vmcnt(5)
	ds_write_b128 v102, v[52:55]
	s_waitcnt vmcnt(4)
	ds_write_b128 v151, v[56:59]
	s_waitcnt vmcnt(3)
	ds_write_b128 v104, v[60:63]
	s_waitcnt vmcnt(2)
	ds_write_b128 v152, v[64:67]
	s_waitcnt vmcnt(1)
	ds_write_b128 v106, v[72:75]
	s_waitcnt vmcnt(0)
	ds_write_b128 v153, v[76:79]
	v_lshl_or_b32 v1, s22, 6, v111
	v_or_b32_e32 v144, s2, v1
	v_lshlrev_b64 v[140:141], 11, v[144:145]
	v_lshl_add_u64 v[88:89], v[142:143], 0, v[140:141]
	s_waitcnt lgkmcnt(0)
	s_barrier
	global_load_dwordx4 v[20:23], v[88:89], off
	global_load_dwordx4 v[24:27], v[88:89], off offset:64
	v_mad_u32_u24 v4, v0, s59, v117
	ds_read_b128 v[0:3], v4
	ds_read_b128 v[4:7], v4 offset:64
	s_waitcnt vmcnt(1) lgkmcnt(1)
	v_mfma_f32_16x16x32_bf16 v[0:3], v[0:3], v[20:23], 0
	s_waitcnt vmcnt(0) lgkmcnt(0)
	v_mfma_f32_16x16x32_bf16 v[28:31], v[4:7], v[24:27], v[0:3]
	s_nop 5
	v_or_b32_e32 v0, s35, v119
	v_mad_u32_u24 v4, v0, s59, v117
	ds_read_b128 v[0:3], v4
	ds_read_b128 v[4:7], v4 offset:64
	s_waitcnt lgkmcnt(1)
	v_mfma_f32_16x16x32_bf16 v[0:3], v[0:3], v[20:23], 0
	s_waitcnt lgkmcnt(0)
	v_mfma_f32_16x16x32_bf16 v[32:35], v[4:7], v[24:27], v[0:3]
	s_nop 5
	v_add_u32_e32 v0, s34, v115
	v_mad_u32_u24 v4, v0, s59, v117
	ds_read_b128 v[0:3], v4
	ds_read_b128 v[4:7], v4 offset:64
	s_waitcnt lgkmcnt(1)
	v_mfma_f32_16x16x32_bf16 v[0:3], v[0:3], v[20:23], 0
	s_waitcnt lgkmcnt(0)
	v_mfma_f32_16x16x32_bf16 v[36:39], v[4:7], v[24:27], v[0:3]
	s_nop 5
	v_add_u32_e32 v0, s34, v119
	v_mad_u32_u24 v4, v0, s59, v117
	ds_read_b128 v[0:3], v4
	ds_read_b128 v[4:7], v4 offset:64
	s_waitcnt lgkmcnt(1)
	v_mfma_f32_16x16x32_bf16 v[0:3], v[0:3], v[20:23], 0
	s_waitcnt lgkmcnt(0)
	v_mfma_f32_16x16x32_bf16 v[16:19], v[4:7], v[24:27], v[0:3]
	s_nop 5
	v_or_b32_e32 v0, s33, v115
	v_mad_u32_u24 v4, v0, s59, v117
	ds_read_b128 v[0:3], v4
	ds_read_b128 v[4:7], v4 offset:64
	s_waitcnt lgkmcnt(1)
	v_mfma_f32_16x16x32_bf16 v[0:3], v[0:3], v[20:23], 0
	s_waitcnt lgkmcnt(0)
	v_mfma_f32_16x16x32_bf16 v[12:15], v[4:7], v[24:27], v[0:3]
	s_nop 5
	v_add_u32_e32 v0, s33, v119
	v_mad_u32_u24 v4, v0, s59, v117
	ds_read_b128 v[0:3], v4
	ds_read_b128 v[4:7], v4 offset:64
	s_waitcnt lgkmcnt(1)
	v_mfma_f32_16x16x32_bf16 v[0:3], v[0:3], v[20:23], 0
	s_waitcnt lgkmcnt(0)
	v_mfma_f32_16x16x32_bf16 v[8:11], v[4:7], v[24:27], v[0:3]
	s_nop 5
	v_add_u32_e32 v0, s26, v115
	v_mad_u32_u24 v4, v0, s59, v117
	ds_read_b128 v[0:3], v4
	ds_read_b128 v[4:7], v4 offset:64
	s_waitcnt lgkmcnt(1)
	v_mfma_f32_16x16x32_bf16 v[0:3], v[0:3], v[20:23], 0
	s_waitcnt lgkmcnt(0)
	v_mfma_f32_16x16x32_bf16 v[4:7], v[4:7], v[24:27], v[0:3]
	s_nop 5
	v_add_u32_e32 v0, s26, v119
	v_mad_u32_u24 v40, v0, s59, v117
	ds_read_b128 v[0:3], v40
	ds_read_b128 v[40:43], v40 offset:64
	s_waitcnt lgkmcnt(1)
	v_mfma_f32_16x16x32_bf16 v[0:3], v[0:3], v[20:23], 0
	global_load_dword v194, v98, s[20:21] offset:868
	global_load_dword v195, v99, s[20:21] offset:868
	global_load_dword v196, v97, s[20:21] offset:868
	global_load_dword v197, v95, s[20:21] offset:868
	global_load_dword v198, v93, s[20:21] offset:868
	global_load_dword v199, v96, s[20:21] offset:868
	global_load_dword v200, v97, s[20:21] offset:992
	global_load_dword v201, v93, s[20:21] offset:992
	global_load_dword v202, v92, s[20:21] offset:868
	global_load_dword v203, v95, s[20:21] offset:992
	global_load_dword v204, v98, s[20:21] offset:992
	global_load_dword v205, v94, s[20:21] offset:868
	global_load_dword v206, v92, s[20:21] offset:992
	global_load_dword v207, v99, s[20:21] offset:1116
	global_load_dword v208, v96, s[20:21] offset:1116
	global_load_dword v209, v98, s[20:21] offset:1116
	global_load_dword v210, v94, s[20:21] offset:1116
	global_load_dword v211, v97, s[20:21] offset:1116
	global_load_dword v212, v93, s[20:21] offset:1116
	global_load_dword v213, v96, s[20:21] offset:992
	global_load_dword v226, v95, s[20:21] offset:1116
	global_load_dword v227, v92, s[20:21] offset:1116
	global_load_dword v228, v94, s[20:21] offset:992
	global_load_dword v229, v99, s[20:21] offset:1240
	global_load_dword v230, v96, s[20:21] offset:1240
	global_load_dword v231, v98, s[20:21] offset:1240
	global_load_dword v232, v94, s[20:21] offset:1240
	global_load_dword v233, v99, s[20:21] offset:992
	global_load_dword v234, v97, s[20:21] offset:1240
	global_load_dword v235, v93, s[20:21] offset:1240
	global_load_dword v236, v95, s[20:21] offset:1240
	global_load_dword v237, v92, s[20:21] offset:1240
	s_waitcnt lgkmcnt(0)
	v_mfma_f32_16x16x32_bf16 v[0:3], v[40:43], v[24:27], v[0:3]
	s_waitcnt vmcnt(0)
	v_fmamk_f32 v24, v196, 0x3fb8aa3b, v32
	v_cndmask_b32_e64 v24, v220, v24, s[46:47]
	v_fmamk_f32 v16, v200, 0x3fb8aa3b, v16
	v_fmamk_f32 v26, v197, 0x3fb8aa3b, v34
	v_cndmask_b32_e64 v27, v220, v26, s[50:51]
	v_cndmask_b32_e64 v16, v220, v16, s[46:47]
	v_fmamk_f32 v17, v201, 0x3fb8aa3b, v17
	v_fmamk_f32 v22, v194, 0x3fb8aa3b, v30
	v_cndmask_b32_e64 v23, v220, v22, s[42:43]
	v_cndmask_b32_e64 v17, v220, v17, s[48:49]
	v_fmamk_f32 v18, v203, 0x3fb8aa3b, v18
	v_cndmask_b32_e64 v32, v220, v18, s[50:51]
	v_fmac_f32_e32 v35, 0x3fb8aa3b, v202
	v_fmamk_f32 v25, v198, 0x3fb8aa3b, v33
	v_cndmask_b32_e64 v26, v220, v35, s[52:53]
	v_cndmask_b32_e64 v25, v220, v25, s[48:49]
	v_max_f32_e32 v33, v27, v26
	v_max3_f32 v33, v24, v25, v33
	v_fmac_f32_e32 v19, 0x3fb8aa3b, v206
	v_cndmask_b32_e64 v18, v220, v19, s[52:53]
	v_max_f32_e32 v34, v32, v18
	v_max3_f32 v34, v16, v17, v34
	v_fmamk_f32 v12, v207, 0x3fb8aa3b, v12
	v_cndmask_b32_e64 v12, v220, v12, s[38:39]
	v_fmamk_f32 v13, v208, 0x3fb8aa3b, v13
	v_cndmask_b32_e64 v13, v220, v13, s[40:41]
	v_fmamk_f32 v14, v209, 0x3fb8aa3b, v14
	v_cndmask_b32_e64 v19, v220, v14, s[42:43]
	v_fmamk_f32 v30, v204, 0x3fb8aa3b, v38
	v_fmac_f32_e32 v15, 0x3fb8aa3b, v210
	v_cndmask_b32_e64 v14, v220, v15, s[44:45]
	v_fmamk_f32 v8, v211, 0x3fb8aa3b, v8
	v_fmamk_f32 v21, v199, 0x3fb8aa3b, v29
	v_cndmask_b32_e64 v21, v220, v21, s[40:41]
	v_cndmask_b32_e64 v8, v220, v8, s[46:47]
	v_fmamk_f32 v9, v212, 0x3fb8aa3b, v9
	v_cndmask_b32_e64 v9, v220, v9, s[48:49]
	v_fmamk_f32 v10, v226, 0x3fb8aa3b, v10
	v_cndmask_b32_e64 v15, v220, v10, s[50:51]
	v_fmac_f32_e32 v31, 0x3fb8aa3b, v205
	v_cndmask_b32_e64 v22, v220, v31, s[44:45]
	v_cndmask_b32_e64 v31, v220, v30, s[42:43]
	v_fmac_f32_e32 v11, 0x3fb8aa3b, v227
	v_cndmask_b32_e64 v10, v220, v11, s[52:53]
	v_fmamk_f32 v4, v229, 0x3fb8aa3b, v4
	v_cndmask_b32_e64 v4, v220, v4, s[38:39]
	v_fmamk_f32 v5, v230, 0x3fb8aa3b, v5
	v_cndmask_b32_e64 v5, v220, v5, s[40:41]
	v_fmamk_f32 v6, v231, 0x3fb8aa3b, v6
	v_fmamk_f32 v20, v195, 0x3fb8aa3b, v28
	v_cndmask_b32_e64 v20, v220, v20, s[38:39]
	v_cndmask_b32_e64 v6, v220, v6, s[42:43]
	v_fmac_f32_e32 v7, 0x3fb8aa3b, v232
	v_cndmask_b32_e64 v7, v220, v7, s[44:45]
	v_fmamk_f32 v0, v234, 0x3fb8aa3b, v0
	v_fmamk_f32 v29, v213, 0x3fb8aa3b, v37
	v_cndmask_b32_e64 v29, v220, v29, s[40:41]
	v_cndmask_b32_e64 v0, v220, v0, s[46:47]
	v_fmamk_f32 v1, v235, 0x3fb8aa3b, v1
	v_fmamk_f32 v28, v233, 0x3fb8aa3b, v36
	v_cndmask_b32_e64 v28, v220, v28, s[38:39]
	v_cndmask_b32_e64 v1, v220, v1, s[48:49]
	v_fmamk_f32 v2, v236, 0x3fb8aa3b, v2
	v_fmac_f32_e32 v39, 0x3fb8aa3b, v228
	v_cndmask_b32_e64 v30, v220, v39, s[44:45]
	s_mov_b32 s20, 0xf149f2ca
	v_cndmask_b32_e64 v2, v220, v2, s[50:51]
	v_fmac_f32_e32 v3, 0x3fb8aa3b, v237
	v_max_f32_e32 v11, v23, v22
	v_max3_f32 v11, v20, v21, v11
	v_max3_f32 v11, v11, s20, v33
	v_max_f32_e32 v33, v31, v30
	v_max3_f32 v33, v28, v29, v33
	v_max3_f32 v11, v11, v33, v34
	v_max_f32_e32 v33, v19, v14
	v_max_f32_e32 v34, v15, v10
	v_cndmask_b32_e64 v3, v220, v3, s[52:53]
	v_max3_f32 v33, v12, v13, v33
	v_max3_f32 v34, v8, v9, v34
	v_max3_f32 v11, v11, v33, v34
	v_max_f32_e32 v33, v6, v7
	v_max_f32_e32 v34, v2, v3
	v_max3_f32 v33, v4, v5, v33
	v_max3_f32 v34, v0, v1, v34
	v_max3_f32 v11, v11, v33, v34
	v_and_b32_e32 v34, 64, v219
	v_xor_b32_e32 v33, 16, v219
	v_add_u32_e32 v34, 64, v34
	v_cmp_lt_i32_e32 vcc, v33, v34
	s_nop 1
	v_cndmask_b32_e32 v33, v219, v33, vcc
	v_lshlrev_b32_e32 v145, 2, v33
	ds_bpermute_b32 v33, v145, v11
	s_waitcnt lgkmcnt(0)
	v_max_f32_e32 v33, v33, v33
	v_max_f32_e32 v11, v11, v33
	v_xor_b32_e32 v33, 32, v219
	v_cmp_lt_i32_e32 vcc, v33, v34
	s_nop 1
	v_cndmask_b32_e32 v33, v219, v33, vcc
	v_lshlrev_b32_e32 v149, 2, v33
	ds_bpermute_b32 v33, v149, v11
	s_waitcnt lgkmcnt(0)
	v_max3_f32 v146, v11, v33, s20
	v_sub_f32_e32 v20, v20, v146
	v_exp_f32_e32 v33, v20
	v_sub_f32_e32 v21, v21, v146
	v_exp_f32_e32 v34, v21
	v_sub_f32_e32 v21, v23, v146
	v_exp_f32_e32 v35, v21
	v_sub_f32_e32 v21, v22, v146
	v_exp_f32_e32 v36, v21
	v_sub_f32_e32 v21, v24, v146
	v_add_f32_e32 v20, 0, v33
	v_exp_f32_e32 v24, v21
	v_sub_f32_e32 v21, v25, v146
	v_add_f32_e32 v20, v34, v20
	v_exp_f32_e32 v25, v21
	v_sub_f32_e32 v21, v27, v146
	v_add_f32_e32 v20, v35, v20
	v_exp_f32_e32 v27, v21
	v_sub_f32_e32 v21, v26, v146
	v_add_f32_e32 v20, v36, v20
	v_exp_f32_e32 v26, v21
	v_sub_f32_e32 v21, v28, v146
	v_add_f32_e32 v20, v24, v20
	v_exp_f32_e32 v28, v21
	v_sub_f32_e32 v21, v29, v146
	v_add_f32_e32 v20, v25, v20
	v_exp_f32_e32 v29, v21
	v_sub_f32_e32 v21, v31, v146
	v_add_f32_e32 v20, v27, v20
	v_exp_f32_e32 v31, v21
	v_sub_f32_e32 v21, v30, v146
	v_add_f32_e32 v20, v26, v20
	v_exp_f32_e32 v30, v21
	v_sub_f32_e32 v16, v16, v146
	v_add_f32_e32 v20, v28, v20
	v_exp_f32_e32 v37, v16
	v_sub_f32_e32 v17, v17, v146
	v_add_f32_e32 v20, v29, v20
	v_exp_f32_e32 v38, v17
	v_sub_f32_e32 v17, v32, v146
	v_add_f32_e32 v20, v31, v20
	v_exp_f32_e32 v32, v17
	v_sub_f32_e32 v17, v18, v146
	v_add_f32_e32 v20, v30, v20
	v_exp_f32_e32 v39, v17
	v_sub_f32_e32 v12, v12, v146
	v_add_f32_e32 v16, v37, v20
	v_exp_f32_e32 v40, v12
	v_sub_f32_e32 v13, v13, v146
	v_add_f32_e32 v16, v38, v16
	v_exp_f32_e32 v41, v13
	v_sub_f32_e32 v13, v19, v146
	v_add_f32_e32 v16, v32, v16
	v_exp_f32_e32 v42, v13
	v_sub_f32_e32 v13, v14, v146
	v_add_f32_e32 v16, v39, v16
	v_exp_f32_e32 v43, v13
	v_sub_f32_e32 v8, v8, v146
	v_add_f32_e32 v12, v40, v16
	v_exp_f32_e32 v44, v8
	v_sub_f32_e32 v9, v9, v146
	v_add_f32_e32 v12, v41, v12
	v_exp_f32_e32 v45, v9
	v_sub_f32_e32 v9, v15, v146
	v_add_f32_e32 v12, v42, v12
	v_exp_f32_e32 v46, v9
	v_sub_f32_e32 v9, v10, v146
	v_add_f32_e32 v12, v43, v12
	v_exp_f32_e32 v47, v9
	v_sub_f32_e32 v4, v4, v146
	v_add_f32_e32 v8, v44, v12
	v_exp_f32_e32 v48, v4
	v_sub_f32_e32 v5, v5, v146
	v_add_f32_e32 v8, v45, v8
	v_exp_f32_e32 v49, v5
	v_sub_f32_e32 v5, v6, v146
	v_add_f32_e32 v8, v46, v8
	v_exp_f32_e32 v50, v5
	v_sub_f32_e32 v5, v7, v146
	v_add_f32_e32 v8, v47, v8
	v_exp_f32_e32 v51, v5
	v_sub_f32_e32 v0, v0, v146
	v_add_f32_e32 v4, v48, v8
	v_exp_f32_e32 v52, v0
	v_sub_f32_e32 v1, v1, v146
	v_add_f32_e32 v4, v49, v4
	v_exp_f32_e32 v53, v1
	v_sub_f32_e32 v1, v2, v146
	v_add_f32_e32 v4, v50, v4
	v_exp_f32_e32 v54, v1
	v_sub_f32_e32 v1, v3, v146
	v_add_f32_e32 v4, v51, v4
	v_exp_f32_e32 v55, v1
	v_add_f32_e32 v0, v52, v4
	v_add_f32_e32 v0, v53, v0
	v_add_f32_e32 v0, v54, v0
	v_add_f32_e32 v0, v55, v0
	v_sub_f32_e32 v11, 0xf149f2ca, v146
	ds_bpermute_b32 v2, v145, v0
	v_exp_f32_e32 v1, v11
	s_or_b32 s20, s35, s60
	v_lshl_add_u32 v16, s20, 1, v121
	v_add_u32_e32 v12, v16, v123
	s_waitcnt lgkmcnt(0)
	v_add_f32_e32 v90, v0, v2
	v_mul_f32_e32 v20, 0, v1
	v_cvt_pk_bf16_f32 v0, v33, v34
	v_cvt_pk_bf16_f32 v1, v35, v36
	v_cvt_pk_bf16_f32 v2, v24, v25
	v_cvt_pk_bf16_f32 v3, v27, v26
	ds_read2_b64 v[4:7], v12 offset1:4
	v_add_u32_e32 v8, 0x4000, v12
	v_add_u32_e32 v12, 0x8000, v12
	v_add_u32_e32 v16, v16, v125
	ds_read2_b64 v[8:11], v8 offset0:32 offset1:36
	ds_read2_b64 v[12:15], v12 offset0:64 offset1:68
	ds_read2_b64 v[16:19], v16 offset1:4
	v_mov_b32_e32 v21, v20
	v_mov_b32_e32 v22, v20
	v_mov_b32_e32 v23, v20
	s_or_b32 s20, s34, s60
	ds_bpermute_b32 v91, v149, v90
	s_waitcnt lgkmcnt(4)
	v_mfma_f32_16x16x32_bf16 v[4:7], v[4:7], v[0:3], v[20:23]
	s_waitcnt lgkmcnt(3)
	v_mfma_f32_16x16x32_bf16 v[8:11], v[8:11], v[0:3], v[20:23]
	s_waitcnt lgkmcnt(2)
	v_mfma_f32_16x16x32_bf16 v[12:15], v[12:15], v[0:3], v[20:23]
	s_waitcnt lgkmcnt(1)
	v_mfma_f32_16x16x32_bf16 v[0:3], v[16:19], v[0:3], v[20:23]
	v_cvt_pk_bf16_f32 v16, v28, v29
	v_cvt_pk_bf16_f32 v17, v31, v30
	v_cvt_pk_bf16_f32 v18, v37, v38
	v_cvt_pk_bf16_f32 v19, v32, v39
	s_nop 2
	v_lshl_add_u32 v21, s20, 1, v121
	v_add_u32_e32 v26, v21, v123
	ds_read2_b64 v[22:25], v26 offset1:4
	s_waitcnt lgkmcnt(0)
	v_mfma_f32_16x16x32_bf16 v[4:7], v[22:25], v[16:19], v[4:7]
	v_add_u32_e32 v22, 0x4000, v26
	ds_read2_b64 v[22:25], v22 offset0:32 offset1:36
	v_add_u32_e32 v21, v21, v125
	s_waitcnt lgkmcnt(0)
	v_mfma_f32_16x16x32_bf16 v[8:11], v[22:25], v[16:19], v[8:11]
	v_add_u32_e32 v22, 0x8000, v26
	ds_read2_b64 v[22:25], v22 offset0:64 offset1:68
	s_or_b32 s20, s33, s60
	s_waitcnt lgkmcnt(0)
	v_mfma_f32_16x16x32_bf16 v[12:15], v[22:25], v[16:19], v[12:15]
	ds_read2_b64 v[22:25], v21 offset1:4
	v_lshl_add_u32 v21, s20, 1, v121
	v_add_u32_e32 v26, v21, v123
	s_waitcnt lgkmcnt(0)
	v_mfma_f32_16x16x32_bf16 v[0:3], v[22:25], v[16:19], v[0:3]
	v_cvt_pk_bf16_f32 v16, v40, v41
	v_cvt_pk_bf16_f32 v17, v42, v43
	v_cvt_pk_bf16_f32 v18, v44, v45
	v_cvt_pk_bf16_f32 v19, v46, v47
	ds_read2_b64 v[22:25], v26 offset1:4
	s_waitcnt lgkmcnt(0)
	v_mfma_f32_16x16x32_bf16 v[4:7], v[22:25], v[16:19], v[4:7]
	v_add_u32_e32 v22, 0x4000, v26
	ds_read2_b64 v[22:25], v22 offset0:32 offset1:36
	v_add_u32_e32 v21, v21, v125
	s_waitcnt lgkmcnt(0)
	v_mfma_f32_16x16x32_bf16 v[8:11], v[22:25], v[16:19], v[8:11]
	v_add_u32_e32 v22, 0x8000, v26
	ds_read2_b64 v[22:25], v22 offset0:64 offset1:68
	s_or_b32 s20, s26, s60
	s_waitcnt lgkmcnt(0)
	v_mfma_f32_16x16x32_bf16 v[12:15], v[22:25], v[16:19], v[12:15]
	ds_read2_b64 v[22:25], v21 offset1:4
	v_lshl_add_u32 v21, s20, 1, v121
	v_add_u32_e32 v26, v21, v123
	s_waitcnt lgkmcnt(0)
	v_mfma_f32_16x16x32_bf16 v[0:3], v[22:25], v[16:19], v[0:3]
	v_cvt_pk_bf16_f32 v16, v48, v49
	v_cvt_pk_bf16_f32 v17, v50, v51
	v_cvt_pk_bf16_f32 v18, v52, v53
	v_cvt_pk_bf16_f32 v19, v54, v55
	ds_read2_b64 v[22:25], v26 offset1:4
	s_waitcnt lgkmcnt(0)
	v_mfma_f32_16x16x32_bf16 v[4:7], v[22:25], v[16:19], v[4:7]
	v_add_u32_e32 v22, 0x4000, v26
	ds_read2_b64 v[22:25], v22 offset0:32 offset1:36
	v_add_u32_e32 v21, v21, v125
	s_waitcnt lgkmcnt(0)
	v_mfma_f32_16x16x32_bf16 v[8:11], v[22:25], v[16:19], v[8:11]
	v_add_u32_e32 v22, 0x8000, v26
	ds_read2_b64 v[22:25], v22 offset0:64 offset1:68
	s_or_b32 s20, s22, 1
	s_waitcnt lgkmcnt(0)
	v_mfma_f32_16x16x32_bf16 v[12:15], v[22:25], v[16:19], v[12:15]
	ds_read2_b64 v[22:25], v21 offset1:4
	s_waitcnt lgkmcnt(0)
	v_mfma_f32_16x16x32_bf16 v[16:19], v[22:25], v[16:19], v[0:3]
	s_nop 2
	v_sub_u32_e64 v0, s20, 4 clamp
	s_nop 0
	v_readfirstlane_b32 s21, v0
	s_min_u32 s21, s21, 8
	v_sub_u32_e64 v0, s20, 5 clamp
	v_cmp_ne_u32_e32 vcc, s21, v0
	s_cbranch_vccz .LBB0_120
	s_lshl_b32 s26, s21, 6
	s_add_i32 s33, s26, 0x1c0
	v_add_u32_e32 v0, s33, v108
	v_ashrrev_i32_e32 v1, 31, v0
	v_lshlrev_b64 v[0:1], 11, v[0:1]
	s_lshl_b32 s26, s21, 7
	v_lshl_add_u64 v[0:1], v[70:71], 0, v[0:1]
	v_lshl_add_u64 v[22:23], v[68:69], 0, s[26:27]
	s_barrier
	global_load_dwordx4 v[0:3], v[0:1], off
	s_nop 0
	global_load_dwordx4 v[22:25], v[22:23], off offset:896
	s_and_b32 s26, s33, 0x1c0
	v_add_u32_e32 v21, s26, v108
	v_mad_u64_u32 v[26:27], s[34:35], v21, s59, v[110:111]
	v_lshl_add_u32 v28, s26, 1, v109
	s_waitcnt vmcnt(1)
	ds_write_b128 v26, v[0:3]
	s_waitcnt vmcnt(0)
	ds_write_b128 v28, v[22:25]
	s_waitcnt lgkmcnt(0)
	s_barrier
.LBB0_120:
	v_lshl_or_b32 v0, s20, 6, v111
	v_or_b32_e32 v0, s2, v0
	v_mov_b32_e32 v1, s3
	v_lshlrev_b64 v[0:1], 11, v[0:1]
	v_lshl_add_u64 v[22:23], v[142:143], 0, v[0:1]
	global_load_dwordx4 v[0:3], v[22:23], off
	global_load_dwordx4 v[50:53], v[22:23], off offset:64
	s_add_i32 s21, s21, s61
	s_sub_i32 s20, s21, s20
	s_lshl_b32 s21, s21, 6
	s_and_b32 s35, s21, 0x1c0
	v_add_u32_e32 v21, s35, v115
	v_mad_u32_u24 v21, v21, s59, v117
	ds_read_b128 v[22:25], v21
	ds_read_b128 v[26:29], v21 offset:64
	v_add_u32_e32 v21, s35, v119
	v_mad_u32_u24 v21, v21, s59, v117
	s_add_i32 s26, s21, 64
	s_and_b32 s34, s26, 0x1c0
	s_and_b32 s33, s21, 0x140
	s_bitset1_b32 s33, 7
	s_addk_i32 s21, 0xc0
	s_and_b32 s26, s21, 0x1c0
	s_mul_i32 s20, s20, 31
	s_ashr_i32 s21, s20, 31
	s_lshl_b64 s[20:21], s[20:21], 2
	s_add_u32 s20, s36, s20
	s_addc_u32 s21, s23, s21
	s_waitcnt vmcnt(1) lgkmcnt(1)
	v_mfma_f32_16x16x32_bf16 v[22:25], v[22:25], v[0:3], 0
	s_waitcnt vmcnt(0) lgkmcnt(0)
	v_mfma_f32_16x16x32_bf16 v[46:49], v[26:29], v[50:53], v[22:25]
	s_nop 5
	ds_read_b128 v[22:25], v21
	ds_read_b128 v[26:29], v21 offset:64
	v_add_u32_e32 v21, s34, v115
	s_waitcnt lgkmcnt(1)
	v_mfma_f32_16x16x32_bf16 v[22:25], v[22:25], v[0:3], 0
	v_mad_u32_u24 v21, v21, s59, v117
	s_waitcnt lgkmcnt(0)
	v_mfma_f32_16x16x32_bf16 v[38:41], v[26:29], v[50:53], v[22:25]
	s_nop 4
	ds_read_b128 v[22:25], v21
	ds_read_b128 v[26:29], v21 offset:64
	v_add_u32_e32 v21, s34, v119
	v_mad_u32_u24 v21, v21, s59, v117
	s_waitcnt lgkmcnt(1)
	v_mfma_f32_16x16x32_bf16 v[22:25], v[22:25], v[0:3], 0
	s_waitcnt lgkmcnt(0)
	v_mfma_f32_16x16x32_bf16 v[42:45], v[26:29], v[50:53], v[22:25]
	s_nop 5
	ds_read_b128 v[22:25], v21
	ds_read_b128 v[26:29], v21 offset:64
	v_add_u32_e32 v21, s33, v115
	s_waitcnt lgkmcnt(1)
	v_mfma_f32_16x16x32_bf16 v[22:25], v[22:25], v[0:3], 0
	v_mad_u32_u24 v21, v21, s59, v117
	s_waitcnt lgkmcnt(0)
	v_mfma_f32_16x16x32_bf16 v[30:33], v[26:29], v[50:53], v[22:25]
	s_nop 4
	ds_read_b128 v[22:25], v21
	ds_read_b128 v[26:29], v21 offset:64
	v_add_u32_e32 v21, s33, v119
	v_mad_u32_u24 v21, v21, s59, v117
	s_waitcnt lgkmcnt(1)
	v_mfma_f32_16x16x32_bf16 v[22:25], v[22:25], v[0:3], 0
	s_waitcnt lgkmcnt(0)
	v_mfma_f32_16x16x32_bf16 v[34:37], v[26:29], v[50:53], v[22:25]
	s_nop 5
	ds_read_b128 v[22:25], v21
	ds_read_b128 v[26:29], v21 offset:64
	v_add_u32_e32 v21, s26, v115
	s_waitcnt lgkmcnt(1)
	v_mfma_f32_16x16x32_bf16 v[22:25], v[22:25], v[0:3], 0
	v_mad_u32_u24 v21, v21, s59, v117
	s_waitcnt lgkmcnt(0)
	v_mfma_f32_16x16x32_bf16 v[22:25], v[26:29], v[50:53], v[22:25]
	ds_read_b128 v[26:29], v21
	ds_read_b128 v[54:57], v21 offset:64
	v_add_u32_e32 v21, s26, v119
	v_mad_u32_u24 v21, v21, s59, v117
	s_waitcnt lgkmcnt(1)
	v_mfma_f32_16x16x32_bf16 v[26:29], v[26:29], v[0:3], 0
	s_waitcnt lgkmcnt(0)
	v_mfma_f32_16x16x32_bf16 v[26:29], v[54:57], v[50:53], v[26:29]
	ds_read_b128 v[54:57], v21
	ds_read_b128 v[58:61], v21 offset:64
	global_load_dword v194, v99, s[20:21] offset:868
	global_load_dword v195, v96, s[20:21] offset:868
	global_load_dword v196, v98, s[20:21] offset:868
	global_load_dword v197, v94, s[20:21] offset:868
	global_load_dword v198, v97, s[20:21] offset:868
	global_load_dword v199, v93, s[20:21] offset:868
	global_load_dword v200, v95, s[20:21] offset:868
	global_load_dword v201, v92, s[20:21] offset:868
	global_load_dword v202, v99, s[20:21] offset:992
	global_load_dword v203, v96, s[20:21] offset:992
	global_load_dword v204, v98, s[20:21] offset:992
	global_load_dword v205, v94, s[20:21] offset:992
	global_load_dword v206, v97, s[20:21] offset:992
	global_load_dword v207, v93, s[20:21] offset:992
	global_load_dword v208, v95, s[20:21] offset:992
	global_load_dword v209, v92, s[20:21] offset:992
	global_load_dword v210, v99, s[20:21] offset:1116
	global_load_dword v211, v96, s[20:21] offset:1116
	global_load_dword v212, v98, s[20:21] offset:1116
	global_load_dword v213, v94, s[20:21] offset:1116
	global_load_dword v226, v97, s[20:21] offset:1116
	global_load_dword v227, v93, s[20:21] offset:1116
	global_load_dword v228, v95, s[20:21] offset:1116
	global_load_dword v229, v92, s[20:21] offset:1116
	global_load_dword v230, v99, s[20:21] offset:1240
	global_load_dword v231, v96, s[20:21] offset:1240
	global_load_dword v232, v98, s[20:21] offset:1240
	global_load_dword v233, v97, s[20:21] offset:1240
	global_load_dword v234, v93, s[20:21] offset:1240
	global_load_dword v235, v94, s[20:21] offset:1240
	global_load_dword v236, v95, s[20:21] offset:1240
	global_load_dword v237, v92, s[20:21] offset:1240
	s_waitcnt lgkmcnt(1)
	v_mfma_f32_16x16x32_bf16 v[0:3], v[54:57], v[0:3], 0
	s_waitcnt vmcnt(0)
	v_fmamk_f32 v21, v194, 0x3fb8aa3b, v46
	s_waitcnt lgkmcnt(0)
	v_mfma_f32_16x16x32_bf16 v[0:3], v[58:61], v[50:53], v[0:3]
	v_cndmask_b32_e64 v21, v220, v21, s[38:39]
	v_fmamk_f32 v46, v195, 0x3fb8aa3b, v47
	v_cndmask_b32_e64 v46, v220, v46, s[40:41]
	v_fmamk_f32 v47, v196, 0x3fb8aa3b, v48
	v_cndmask_b32_e64 v48, v220, v47, s[42:43]
	v_fmac_f32_e32 v49, 0x3fb8aa3b, v197
	v_cndmask_b32_e64 v47, v220, v49, s[44:45]
	v_fmamk_f32 v38, v198, 0x3fb8aa3b, v38
	v_cndmask_b32_e64 v38, v220, v38, s[46:47]
	v_fmamk_f32 v39, v199, 0x3fb8aa3b, v39
	v_cndmask_b32_e64 v39, v220, v39, s[48:49]
	v_fmamk_f32 v40, v200, 0x3fb8aa3b, v40
	v_cndmask_b32_e64 v49, v220, v40, s[50:51]
	v_fmac_f32_e32 v41, 0x3fb8aa3b, v201
	v_cndmask_b32_e64 v40, v220, v41, s[52:53]
	v_fmamk_f32 v41, v202, 0x3fb8aa3b, v42
	v_cndmask_b32_e64 v41, v220, v41, s[38:39]
	v_fmamk_f32 v42, v203, 0x3fb8aa3b, v43
	v_cndmask_b32_e64 v42, v220, v42, s[40:41]
	v_fmamk_f32 v43, v204, 0x3fb8aa3b, v44
	v_cndmask_b32_e64 v44, v220, v43, s[42:43]
	v_fmac_f32_e32 v45, 0x3fb8aa3b, v205
	v_cndmask_b32_e64 v43, v220, v45, s[44:45]
	v_fmamk_f32 v30, v206, 0x3fb8aa3b, v30
	v_cndmask_b32_e64 v30, v220, v30, s[46:47]
	v_fmamk_f32 v31, v207, 0x3fb8aa3b, v31
	v_cndmask_b32_e64 v31, v220, v31, s[48:49]
	v_fmamk_f32 v32, v208, 0x3fb8aa3b, v32
	v_cndmask_b32_e64 v45, v220, v32, s[50:51]
	v_fmac_f32_e32 v33, 0x3fb8aa3b, v209
	v_cndmask_b32_e64 v32, v220, v33, s[52:53]
	v_max_f32_e32 v51, v45, v32
	v_max3_f32 v51, v30, v31, v51
	v_fmamk_f32 v33, v210, 0x3fb8aa3b, v34
	v_cndmask_b32_e64 v33, v220, v33, s[38:39]
	v_fmamk_f32 v34, v211, 0x3fb8aa3b, v35
	v_cndmask_b32_e64 v34, v220, v34, s[40:41]
	v_fmamk_f32 v35, v212, 0x3fb8aa3b, v36
	v_cndmask_b32_e64 v36, v220, v35, s[42:43]
	v_fmac_f32_e32 v37, 0x3fb8aa3b, v213
	v_cndmask_b32_e64 v35, v220, v37, s[44:45]
	v_fmamk_f32 v22, v226, 0x3fb8aa3b, v22
	v_cndmask_b32_e64 v22, v220, v22, s[46:47]
	v_fmamk_f32 v23, v227, 0x3fb8aa3b, v23
	v_cndmask_b32_e64 v37, v220, v23, s[48:49]
	v_fmamk_f32 v23, v228, 0x3fb8aa3b, v24
	v_cndmask_b32_e64 v50, v220, v23, s[50:51]
	v_fmac_f32_e32 v25, 0x3fb8aa3b, v229
	v_cndmask_b32_e64 v24, v220, v25, s[52:53]
	v_fmamk_f32 v23, v230, 0x3fb8aa3b, v26
	v_cndmask_b32_e64 v23, v220, v23, s[38:39]
	v_fmamk_f32 v26, v232, 0x3fb8aa3b, v28
	v_cndmask_b32_e64 v26, v220, v26, s[42:43]
	v_fmamk_f32 v0, v233, 0x3fb8aa3b, v0
	v_fmamk_f32 v25, v231, 0x3fb8aa3b, v27
	v_cndmask_b32_e64 v25, v220, v25, s[40:41]
	v_cndmask_b32_e64 v0, v220, v0, s[46:47]
	v_fmamk_f32 v1, v234, 0x3fb8aa3b, v1
	v_cndmask_b32_e64 v1, v220, v1, s[48:49]
	v_fmamk_f32 v2, v236, 0x3fb8aa3b, v2
	v_fmac_f32_e32 v29, 0x3fb8aa3b, v235
	v_cndmask_b32_e64 v27, v220, v29, s[44:45]
	v_max_f32_e32 v29, v49, v40
	v_max3_f32 v29, v38, v39, v29
	s_mov_b32 s20, 0xf149f2ca
	v_cndmask_b32_e64 v2, v220, v2, s[50:51]
	v_fmac_f32_e32 v3, 0x3fb8aa3b, v237
	v_max_f32_e32 v28, v48, v47
	v_max3_f32 v28, v21, v46, v28
	v_max3_f32 v28, v28, s20, v29
	v_max_f32_e32 v29, v44, v43
	v_max3_f32 v29, v41, v42, v29
	v_max3_f32 v28, v28, v29, v51
	v_max_f32_e32 v29, v36, v35
	v_max_f32_e32 v51, v50, v24
	v_cndmask_b32_e64 v3, v220, v3, s[52:53]
	v_max3_f32 v29, v33, v34, v29
	v_max3_f32 v51, v22, v37, v51
	v_max3_f32 v28, v28, v29, v51
	v_max_f32_e32 v29, v26, v27
	v_max_f32_e32 v51, v2, v3
	v_max3_f32 v29, v23, v25, v29
	v_max3_f32 v51, v0, v1, v51
	v_max3_f32 v28, v28, v29, v51
	ds_bpermute_b32 v29, v145, v28
	s_waitcnt lgkmcnt(0)
	v_max_f32_e32 v29, v29, v29
	v_max_f32_e32 v28, v28, v29
	ds_bpermute_b32 v29, v149, v28
	s_waitcnt lgkmcnt(0)
	v_max3_f32 v150, v28, v29, s20
	v_sub_f32_e32 v21, v21, v150
	v_exp_f32_e32 v29, v21
	v_sub_f32_e32 v46, v46, v150
	v_exp_f32_e32 v46, v46
	v_sub_f32_e32 v48, v48, v150
	v_exp_f32_e32 v48, v48
	v_sub_f32_e32 v47, v47, v150
	v_exp_f32_e32 v47, v47
	v_sub_f32_e32 v38, v38, v150
	v_add_f32_e32 v21, 0, v29
	v_exp_f32_e32 v38, v38
	v_sub_f32_e32 v39, v39, v150
	v_add_f32_e32 v21, v46, v21
	v_exp_f32_e32 v39, v39
	v_sub_f32_e32 v49, v49, v150
	v_add_f32_e32 v21, v48, v21
	v_exp_f32_e32 v49, v49
	v_sub_f32_e32 v40, v40, v150
	v_add_f32_e32 v21, v47, v21
	v_exp_f32_e32 v40, v40
	v_sub_f32_e32 v41, v41, v150
	v_add_f32_e32 v21, v38, v21
	v_exp_f32_e32 v41, v41
	v_sub_f32_e32 v42, v42, v150
	v_add_f32_e32 v21, v39, v21
	v_exp_f32_e32 v42, v42
	v_sub_f32_e32 v44, v44, v150
	v_add_f32_e32 v21, v49, v21
	v_exp_f32_e32 v44, v44
	v_sub_f32_e32 v43, v43, v150
	v_add_f32_e32 v21, v40, v21
	v_exp_f32_e32 v43, v43
	v_sub_f32_e32 v30, v30, v150
	v_add_f32_e32 v21, v41, v21
	v_exp_f32_e32 v51, v30
	v_sub_f32_e32 v30, v31, v150
	v_add_f32_e32 v21, v42, v21
	v_exp_f32_e32 v52, v30
	v_sub_f32_e32 v30, v45, v150
	v_add_f32_e32 v21, v44, v21
	v_exp_f32_e32 v45, v30
	v_sub_f32_e32 v30, v32, v150
	v_add_f32_e32 v21, v43, v21
	v_exp_f32_e32 v53, v30
	v_sub_f32_e32 v30, v33, v150
	v_add_f32_e32 v21, v51, v21
	v_exp_f32_e32 v54, v30
	v_sub_f32_e32 v30, v34, v150
	v_add_f32_e32 v21, v52, v21
	v_exp_f32_e32 v55, v30
	v_sub_f32_e32 v30, v36, v150
	v_add_f32_e32 v21, v45, v21
	v_exp_f32_e32 v56, v30
	v_sub_f32_e32 v30, v35, v150
	v_add_f32_e32 v21, v53, v21
	v_exp_f32_e32 v57, v30
	v_sub_f32_e32 v22, v22, v150
	v_add_f32_e32 v21, v54, v21
	v_exp_f32_e32 v62, v22
	v_sub_f32_e32 v22, v37, v150
	v_add_f32_e32 v21, v55, v21
	v_exp_f32_e32 v63, v22
	v_sub_f32_e32 v22, v50, v150
	v_add_f32_e32 v21, v56, v21
	v_exp_f32_e32 v50, v22
	v_sub_f32_e32 v22, v24, v150
	v_add_f32_e32 v21, v57, v21
	v_exp_f32_e32 v64, v22
	v_sub_f32_e32 v22, v23, v150
	v_add_f32_e32 v21, v62, v21
	v_exp_f32_e32 v65, v22
	v_sub_f32_e32 v22, v25, v150
	v_add_f32_e32 v21, v63, v21
	v_exp_f32_e32 v66, v22
	v_sub_f32_e32 v22, v26, v150
	v_add_f32_e32 v21, v50, v21
	v_exp_f32_e32 v67, v22
	v_sub_f32_e32 v22, v27, v150
	v_add_f32_e32 v21, v64, v21
	v_exp_f32_e32 v72, v22
	v_sub_f32_e32 v0, v0, v150
	v_add_f32_e32 v21, v65, v21
	v_exp_f32_e32 v73, v0
	v_sub_f32_e32 v1, v1, v150
	v_add_f32_e32 v21, v66, v21
	v_exp_f32_e32 v74, v1
	v_sub_f32_e32 v1, v2, v150
	v_add_f32_e32 v21, v67, v21
	v_exp_f32_e32 v75, v1
	v_sub_f32_e32 v1, v3, v150
	v_add_f32_e32 v21, v72, v21
	v_exp_f32_e32 v76, v1
	v_add_f32_e32 v0, v73, v21
	v_add_f32_e32 v0, v74, v0
	v_add_f32_e32 v0, v75, v0
	v_add_f32_e32 v0, v76, v0
	v_sub_f32_e32 v28, 0xf149f2ca, v150
	ds_bpermute_b32 v2, v145, v0
	v_exp_f32_e32 v1, v28
	s_or_b32 s20, s35, s60
	v_lshl_add_u32 v34, s20, 1, v121
	v_add_u32_e32 v30, v34, v123
	s_waitcnt lgkmcnt(0)
	v_add_f32_e32 v21, v0, v2
	v_mul_f32_e32 v58, 0, v1
	v_cvt_pk_bf16_f32 v0, v29, v46
	v_cvt_pk_bf16_f32 v1, v48, v47
	v_cvt_pk_bf16_f32 v2, v38, v39
	v_cvt_pk_bf16_f32 v3, v49, v40
	ds_read2_b64 v[22:25], v30 offset1:4
	v_add_u32_e32 v26, 0x4000, v30
	v_add_u32_e32 v30, 0x8000, v30
	v_add_u32_e32 v34, v34, v125
	ds_read2_b64 v[26:29], v26 offset0:32 offset1:36
	ds_read2_b64 v[30:33], v30 offset0:64 offset1:68
	ds_read2_b64 v[34:37], v34 offset1:4
	v_mov_b32_e32 v59, v58
	v_mov_b32_e32 v60, v58
	v_mov_b32_e32 v61, v58
	s_or_b32 s20, s34, s60
	ds_bpermute_b32 v100, v149, v21
	s_waitcnt lgkmcnt(4)
	v_mfma_f32_16x16x32_bf16 v[22:25], v[22:25], v[0:3], v[58:61]
	s_waitcnt lgkmcnt(3)
	v_mfma_f32_16x16x32_bf16 v[26:29], v[26:29], v[0:3], v[58:61]
	s_waitcnt lgkmcnt(2)
	v_mfma_f32_16x16x32_bf16 v[30:33], v[30:33], v[0:3], v[58:61]
	s_waitcnt lgkmcnt(1)
	v_mfma_f32_16x16x32_bf16 v[0:3], v[34:37], v[0:3], v[58:61]
	v_cvt_pk_bf16_f32 v34, v41, v42
	v_lshl_add_u32 v42, s20, 1, v121
	v_cvt_pk_bf16_f32 v35, v44, v43
	v_add_u32_e32 v43, v42, v123
	v_cvt_pk_bf16_f32 v36, v51, v52
	v_cvt_pk_bf16_f32 v37, v45, v53
	ds_read2_b64 v[38:41], v43 offset1:4
	s_waitcnt lgkmcnt(0)
	v_mfma_f32_16x16x32_bf16 v[22:25], v[38:41], v[34:37], v[22:25]
	v_add_u32_e32 v38, 0x4000, v43
	ds_read2_b64 v[38:41], v38 offset0:32 offset1:36
	s_or_b32 s20, s33, s60
	s_waitcnt lgkmcnt(0)
	v_mfma_f32_16x16x32_bf16 v[26:29], v[38:41], v[34:37], v[26:29]
	v_add_u32_e32 v38, 0x8000, v43
	ds_read2_b64 v[38:41], v38 offset0:64 offset1:68
	v_lshl_add_u32 v46, s20, 1, v121
	s_waitcnt lgkmcnt(0)
	v_mfma_f32_16x16x32_bf16 v[30:33], v[38:41], v[34:37], v[30:33]
	v_add_u32_e32 v38, v42, v125
	ds_read2_b64 v[38:41], v38 offset1:4
	v_add_u32_e32 v42, v46, v123
	s_waitcnt lgkmcnt(0)
	v_mfma_f32_16x16x32_bf16 v[0:3], v[38:41], v[34:37], v[0:3]
	v_cvt_pk_bf16_f32 v34, v54, v55
	v_cvt_pk_bf16_f32 v35, v56, v57
	v_cvt_pk_bf16_f32 v36, v62, v63
	v_cvt_pk_bf16_f32 v37, v50, v64
	ds_read2_b64 v[38:41], v42 offset1:4
	s_waitcnt lgkmcnt(0)
	v_mfma_f32_16x16x32_bf16 v[22:25], v[38:41], v[34:37], v[22:25]
	v_add_u32_e32 v38, 0x4000, v42
	ds_read2_b64 v[38:41], v38 offset0:32 offset1:36
	s_or_b32 s20, s26, s60
	s_waitcnt lgkmcnt(0)
	v_mfma_f32_16x16x32_bf16 v[38:41], v[38:41], v[34:37], v[26:29]
	s_nop 2
	v_add_u32_e32 v26, 0x8000, v42
	ds_read2_b64 v[26:29], v26 offset0:64 offset1:68
	v_lshl_add_u32 v50, s20, 1, v121
	s_waitcnt lgkmcnt(0)
	v_mfma_f32_16x16x32_bf16 v[42:45], v[26:29], v[34:37], v[30:33]
	v_add_u32_e32 v26, v46, v125
	ds_read2_b64 v[26:29], v26 offset1:4
	v_cvt_pk_bf16_f32 v46, v65, v66
	v_cvt_pk_bf16_f32 v47, v67, v72
	v_cvt_pk_bf16_f32 v48, v73, v74
	s_waitcnt lgkmcnt(0)
	v_mfma_f32_16x16x32_bf16 v[0:3], v[26:29], v[34:37], v[0:3]
	v_add_u32_e32 v34, v50, v123
	v_cvt_pk_bf16_f32 v49, v75, v76
	ds_read2_b64 v[26:29], v34 offset1:4
	s_waitcnt lgkmcnt(0)
	v_mfma_f32_16x16x32_bf16 v[26:29], v[26:29], v[46:49], v[22:25]
	s_nop 2
	v_add_u32_e32 v22, 0x4000, v34
	ds_read2_b64 v[22:25], v22 offset0:32 offset1:36
	s_or_b32 s20, s22, 2
	s_waitcnt lgkmcnt(0)
	v_mfma_f32_16x16x32_bf16 v[30:33], v[22:25], v[46:49], v[38:41]
	v_add_u32_e32 v22, 0x8000, v34
	ds_read2_b64 v[22:25], v22 offset0:64 offset1:68
	s_waitcnt lgkmcnt(0)
	v_mfma_f32_16x16x32_bf16 v[34:37], v[22:25], v[46:49], v[42:45]
	v_add_u32_e32 v22, v50, v125
	ds_read2_b64 v[22:25], v22 offset1:4
	s_waitcnt lgkmcnt(0)
	v_mfma_f32_16x16x32_bf16 v[38:41], v[22:25], v[46:49], v[0:3]
	s_nop 2
	v_sub_u32_e64 v0, s20, 4 clamp
	s_nop 0
	v_readfirstlane_b32 s21, v0
	v_sub_u32_e64 v0, s20, 5 clamp
	s_min_u32 s21, s21, 8
	v_min_u32_e32 v0, 8, v0
	v_cmp_eq_u32_e32 vcc, s21, v0
	s_cbranch_vccnz .LBB0_122
	s_lshl_b32 s26, s21, 6
	s_add_i32 s33, s26, 0x1c0
	v_add_u32_e32 v0, s33, v108
	v_ashrrev_i32_e32 v1, 31, v0
	v_lshlrev_b64 v[0:1], 11, v[0:1]
	s_lshl_b32 s26, s21, 7
	v_lshl_add_u64 v[0:1], v[70:71], 0, v[0:1]
	v_lshl_add_u64 v[22:23], v[68:69], 0, s[26:27]
	s_barrier
	global_load_dwordx4 v[0:3], v[0:1], off
	s_nop 0
	global_load_dwordx4 v[22:25], v[22:23], off offset:896
	s_and_b32 s26, s33, 0x1c0
	v_add_u32_e32 v42, s26, v108
	v_mad_u64_u32 v[42:43], s[34:35], v42, s59, v[110:111]
	v_lshl_add_u32 v44, s26, 1, v109
	s_waitcnt vmcnt(1)
	ds_write_b128 v42, v[0:3]
	s_waitcnt vmcnt(0)
	ds_write_b128 v44, v[22:25]
	s_waitcnt lgkmcnt(0)
	s_barrier
.LBB0_122:
	v_lshl_or_b32 v0, s20, 6, v111
	v_or_b32_e32 v0, s2, v0
	v_mov_b32_e32 v1, s3
	v_lshlrev_b64 v[0:1], 11, v[0:1]
	v_lshl_add_u64 v[22:23], v[142:143], 0, v[0:1]
	global_load_dwordx4 v[0:3], v[22:23], off
	global_load_dwordx4 v[72:75], v[22:23], off offset:64
	s_add_i32 s21, s21, s61
	s_sub_i32 s20, s21, s20
	s_lshl_b32 s21, s21, 6
	s_and_b32 s35, s21, 0x1c0
	v_add_u32_e32 v22, s35, v115
	v_mad_u32_u24 v42, v22, s59, v117
	ds_read_b128 v[22:25], v42
	ds_read_b128 v[42:45], v42 offset:64
	s_and_b32 s26, s21, 0x180
	s_or_b32 s34, s26, 64
	s_add_i32 s26, s21, 0x80
	s_and_b32 s33, s26, 0x1c0
	s_addk_i32 s21, 0xc0
	s_and_b32 s26, s21, 0x1c0
	s_mul_i32 s20, s20, 31
	s_ashr_i32 s21, s20, 31
	s_lshl_b64 s[20:21], s[20:21], 2
	s_add_u32 s20, s36, s20
	s_addc_u32 s21, s23, s21
	v_readlane_b32 s92, v252, 60
	s_mov_b64 s[90:91], s[0:1]
	v_readlane_b32 s93, v252, 61
	s_waitcnt vmcnt(1) lgkmcnt(1)
	v_mfma_f32_16x16x32_bf16 v[22:25], v[22:25], v[0:3], 0
	s_waitcnt vmcnt(0) lgkmcnt(0)
	v_mfma_f32_16x16x32_bf16 v[64:67], v[42:45], v[72:75], v[22:25]
	s_nop 5
	v_add_u32_e32 v22, s35, v119
	v_mad_u32_u24 v42, v22, s59, v117
	ds_read_b128 v[22:25], v42
	ds_read_b128 v[42:45], v42 offset:64
	s_waitcnt lgkmcnt(1)
	v_mfma_f32_16x16x32_bf16 v[22:25], v[22:25], v[0:3], 0
	s_waitcnt lgkmcnt(0)
	v_mfma_f32_16x16x32_bf16 v[54:57], v[42:45], v[72:75], v[22:25]
	s_nop 5
	v_add_u32_e32 v22, s34, v115
	v_mad_u32_u24 v42, v22, s59, v117
	ds_read_b128 v[22:25], v42
	ds_read_b128 v[42:45], v42 offset:64
	s_waitcnt lgkmcnt(1)
	v_mfma_f32_16x16x32_bf16 v[22:25], v[22:25], v[0:3], 0
	s_waitcnt lgkmcnt(0)
	v_mfma_f32_16x16x32_bf16 v[60:63], v[42:45], v[72:75], v[22:25]
	s_nop 5
	v_add_u32_e32 v22, s34, v119
	v_mad_u32_u24 v42, v22, s59, v117
	ds_read_b128 v[22:25], v42
	ds_read_b128 v[42:45], v42 offset:64
	s_waitcnt lgkmcnt(1)
	v_mfma_f32_16x16x32_bf16 v[22:25], v[22:25], v[0:3], 0
	s_waitcnt lgkmcnt(0)
	v_mfma_f32_16x16x32_bf16 v[46:49], v[42:45], v[72:75], v[22:25]
	s_nop 5
	v_add_u32_e32 v22, s33, v115
	v_mad_u32_u24 v42, v22, s59, v117
	ds_read_b128 v[22:25], v42
	ds_read_b128 v[42:45], v42 offset:64
	s_waitcnt lgkmcnt(1)
	v_mfma_f32_16x16x32_bf16 v[22:25], v[22:25], v[0:3], 0
	s_waitcnt lgkmcnt(0)
	v_mfma_f32_16x16x32_bf16 v[50:53], v[42:45], v[72:75], v[22:25]
	s_nop 5
	v_add_u32_e32 v22, s33, v119
	v_mad_u32_u24 v42, v22, s59, v117
	ds_read_b128 v[22:25], v42
	ds_read_b128 v[42:45], v42 offset:64
	s_waitcnt lgkmcnt(1)
	v_mfma_f32_16x16x32_bf16 v[22:25], v[22:25], v[0:3], 0
	s_waitcnt lgkmcnt(0)
	v_mfma_f32_16x16x32_bf16 v[22:25], v[42:45], v[72:75], v[22:25]
	v_add_u32_e32 v42, s26, v115
	v_mad_u32_u24 v59, v42, s59, v117
	ds_read_b128 v[42:45], v59
	ds_read_b128 v[76:79], v59 offset:64
	s_waitcnt lgkmcnt(1)
	v_mfma_f32_16x16x32_bf16 v[42:45], v[42:45], v[0:3], 0
	v_add_u32_e32 v59, s26, v119
	v_mad_u32_u24 v59, v59, s59, v117
	s_waitcnt lgkmcnt(0)
	v_mfma_f32_16x16x32_bf16 v[42:45], v[76:79], v[72:75], v[42:45]
	ds_read_b128 v[76:79], v59
	ds_read_b128 v[80:83], v59 offset:64
	global_load_dword v194, v99, s[20:21] offset:868
	global_load_dword v195, v96, s[20:21] offset:868
	global_load_dword v196, v98, s[20:21] offset:868
	global_load_dword v197, v94, s[20:21] offset:868
	global_load_dword v198, v97, s[20:21] offset:868
	global_load_dword v199, v93, s[20:21] offset:868
	global_load_dword v200, v95, s[20:21] offset:868
	global_load_dword v201, v92, s[20:21] offset:868
	global_load_dword v202, v99, s[20:21] offset:992
	global_load_dword v203, v96, s[20:21] offset:992
	global_load_dword v204, v98, s[20:21] offset:992
	global_load_dword v205, v94, s[20:21] offset:992
	global_load_dword v206, v97, s[20:21] offset:992
	global_load_dword v207, v93, s[20:21] offset:992
	global_load_dword v208, v95, s[20:21] offset:992
	global_load_dword v209, v92, s[20:21] offset:992
	global_load_dword v210, v99, s[20:21] offset:1116
	global_load_dword v211, v96, s[20:21] offset:1116
	global_load_dword v212, v98, s[20:21] offset:1116
	global_load_dword v213, v94, s[20:21] offset:1116
	global_load_dword v226, v97, s[20:21] offset:1116
	global_load_dword v227, v93, s[20:21] offset:1116
	global_load_dword v228, v95, s[20:21] offset:1116
	global_load_dword v229, v92, s[20:21] offset:1116
	global_load_dword v230, v99, s[20:21] offset:1240
	global_load_dword v231, v96, s[20:21] offset:1240
	global_load_dword v232, v98, s[20:21] offset:1240
	global_load_dword v233, v97, s[20:21] offset:1240
	global_load_dword v234, v93, s[20:21] offset:1240
	global_load_dword v235, v94, s[20:21] offset:1240
	global_load_dword v236, v95, s[20:21] offset:1240
	global_load_dword v237, v92, s[20:21] offset:1240
	s_waitcnt lgkmcnt(1)
	v_mfma_f32_16x16x32_bf16 v[0:3], v[76:79], v[0:3], 0
	s_waitcnt vmcnt(0)
	v_fmamk_f32 v59, v194, 0x3fb8aa3b, v64
	s_waitcnt lgkmcnt(0)
	v_mfma_f32_16x16x32_bf16 v[0:3], v[80:83], v[72:75], v[0:3]
	v_cndmask_b32_e64 v59, v220, v59, s[38:39]
	v_fmamk_f32 v64, v195, 0x3fb8aa3b, v65
	v_cndmask_b32_e64 v64, v220, v64, s[40:41]
	v_fmamk_f32 v65, v196, 0x3fb8aa3b, v66
	v_cndmask_b32_e64 v66, v220, v65, s[42:43]
	v_fmac_f32_e32 v67, 0x3fb8aa3b, v197
	v_cndmask_b32_e64 v65, v220, v67, s[44:45]
	v_fmamk_f32 v54, v198, 0x3fb8aa3b, v54
	v_cndmask_b32_e64 v54, v220, v54, s[46:47]
	v_fmamk_f32 v55, v199, 0x3fb8aa3b, v55
	v_cndmask_b32_e64 v55, v220, v55, s[48:49]
	v_fmamk_f32 v56, v200, 0x3fb8aa3b, v56
	v_cndmask_b32_e64 v67, v220, v56, s[50:51]
	v_fmac_f32_e32 v57, 0x3fb8aa3b, v201
	v_cndmask_b32_e64 v56, v220, v57, s[52:53]
	v_fmamk_f32 v57, v202, 0x3fb8aa3b, v60
	v_cndmask_b32_e64 v57, v220, v57, s[38:39]
	v_fmamk_f32 v60, v203, 0x3fb8aa3b, v61
	v_cndmask_b32_e64 v60, v220, v60, s[40:41]
	v_fmamk_f32 v61, v204, 0x3fb8aa3b, v62
	v_cndmask_b32_e64 v62, v220, v61, s[42:43]
	v_fmac_f32_e32 v63, 0x3fb8aa3b, v205
	v_cndmask_b32_e64 v61, v220, v63, s[44:45]
	v_fmamk_f32 v46, v206, 0x3fb8aa3b, v46
	v_cndmask_b32_e64 v46, v220, v46, s[46:47]
	v_fmamk_f32 v47, v207, 0x3fb8aa3b, v47
	v_cndmask_b32_e64 v47, v220, v47, s[48:49]
	v_fmamk_f32 v48, v208, 0x3fb8aa3b, v48
	v_cndmask_b32_e64 v63, v220, v48, s[50:51]
	v_fmac_f32_e32 v49, 0x3fb8aa3b, v209
	v_cndmask_b32_e64 v48, v220, v49, s[52:53]
	v_max_f32_e32 v73, v63, v48
	v_max3_f32 v73, v46, v47, v73
	v_fmamk_f32 v49, v210, 0x3fb8aa3b, v50
	v_cndmask_b32_e64 v49, v220, v49, s[38:39]
	v_fmamk_f32 v50, v211, 0x3fb8aa3b, v51
	v_cndmask_b32_e64 v50, v220, v50, s[40:41]
	v_fmamk_f32 v51, v212, 0x3fb8aa3b, v52
	v_cndmask_b32_e64 v52, v220, v51, s[42:43]
	v_fmac_f32_e32 v53, 0x3fb8aa3b, v213
	v_cndmask_b32_e64 v51, v220, v53, s[44:45]
	v_fmamk_f32 v22, v226, 0x3fb8aa3b, v22
	v_cndmask_b32_e64 v22, v220, v22, s[46:47]
	v_fmamk_f32 v23, v227, 0x3fb8aa3b, v23
	v_cndmask_b32_e64 v53, v220, v23, s[48:49]
	v_fmamk_f32 v23, v228, 0x3fb8aa3b, v24
	v_cndmask_b32_e64 v72, v220, v23, s[50:51]
	v_fmac_f32_e32 v25, 0x3fb8aa3b, v229
	v_cndmask_b32_e64 v24, v220, v25, s[52:53]
	v_fmamk_f32 v23, v230, 0x3fb8aa3b, v42
	v_cndmask_b32_e64 v23, v220, v23, s[38:39]
	v_fmamk_f32 v42, v232, 0x3fb8aa3b, v44
	v_cndmask_b32_e64 v42, v220, v42, s[42:43]
	v_fmamk_f32 v0, v233, 0x3fb8aa3b, v0
	v_fmamk_f32 v25, v231, 0x3fb8aa3b, v43
	v_cndmask_b32_e64 v25, v220, v25, s[40:41]
	v_cndmask_b32_e64 v0, v220, v0, s[46:47]
	v_fmamk_f32 v1, v234, 0x3fb8aa3b, v1
	v_cndmask_b32_e64 v1, v220, v1, s[48:49]
	v_fmamk_f32 v2, v236, 0x3fb8aa3b, v2
	v_fmac_f32_e32 v45, 0x3fb8aa3b, v235
	v_cndmask_b32_e64 v43, v220, v45, s[44:45]
	v_max_f32_e32 v45, v67, v56
	v_max3_f32 v45, v54, v55, v45
	s_mov_b32 s20, 0xf149f2ca
	v_cndmask_b32_e64 v2, v220, v2, s[50:51]
	v_fmac_f32_e32 v3, 0x3fb8aa3b, v237
	v_max_f32_e32 v44, v66, v65
	v_max3_f32 v44, v59, v64, v44
	v_max3_f32 v44, v44, s20, v45
	v_max_f32_e32 v45, v62, v61
	v_max3_f32 v45, v57, v60, v45
	v_max3_f32 v44, v44, v45, v73
	v_max_f32_e32 v45, v52, v51
	v_max_f32_e32 v73, v72, v24
	v_cndmask_b32_e64 v3, v220, v3, s[52:53]
	v_max3_f32 v45, v49, v50, v45
	v_max3_f32 v73, v22, v53, v73
	v_max3_f32 v44, v44, v45, v73
	v_max_f32_e32 v45, v42, v43
	v_max_f32_e32 v73, v2, v3
	v_max3_f32 v45, v23, v25, v45
	v_max3_f32 v73, v0, v1, v73
	v_max3_f32 v44, v44, v45, v73
	ds_bpermute_b32 v45, v145, v44
	s_waitcnt lgkmcnt(0)
	v_max_f32_e32 v45, v45, v45
	v_max_f32_e32 v44, v44, v45
	ds_bpermute_b32 v45, v149, v44
	s_waitcnt lgkmcnt(0)
	v_max3_f32 v153, v44, v45, s20
	v_sub_f32_e32 v45, v59, v153
	v_exp_f32_e32 v45, v45
	v_sub_f32_e32 v64, v64, v153
	v_exp_f32_e32 v64, v64
	v_sub_f32_e32 v66, v66, v153
	v_exp_f32_e32 v66, v66
	v_sub_f32_e32 v65, v65, v153
	v_exp_f32_e32 v65, v65
	v_sub_f32_e32 v54, v54, v153
	v_add_f32_e32 v59, 0, v45
	v_exp_f32_e32 v54, v54
	v_sub_f32_e32 v55, v55, v153
	v_add_f32_e32 v59, v64, v59
	v_exp_f32_e32 v55, v55
	v_sub_f32_e32 v67, v67, v153
	v_add_f32_e32 v59, v66, v59
	v_exp_f32_e32 v67, v67
	v_sub_f32_e32 v56, v56, v153
	v_add_f32_e32 v59, v65, v59
	v_exp_f32_e32 v56, v56
	v_sub_f32_e32 v57, v57, v153
	v_add_f32_e32 v59, v54, v59
	v_exp_f32_e32 v73, v57
	v_add_f32_e32 v59, v55, v59
	v_add_f32_e32 v59, v67, v59
	v_add_f32_e32 v59, v56, v59
	v_add_f32_e32 v57, v73, v59
	v_sub_f32_e32 v59, v60, v153
	v_exp_f32_e32 v59, v59
	v_sub_f32_e32 v60, v62, v153
	v_exp_f32_e32 v60, v60
	v_sub_f32_e32 v61, v61, v153
	v_exp_f32_e32 v61, v61
	v_sub_f32_e32 v46, v46, v153
	v_exp_f32_e32 v62, v46
	v_sub_f32_e32 v47, v47, v153
	v_add_f32_e32 v57, v59, v57
	v_exp_f32_e32 v74, v47
	v_sub_f32_e32 v47, v63, v153
	v_add_f32_e32 v57, v60, v57
	v_exp_f32_e32 v63, v47
	v_sub_f32_e32 v47, v48, v153
	v_add_f32_e32 v57, v61, v57
	v_exp_f32_e32 v75, v47
	v_sub_f32_e32 v47, v49, v153
	v_add_f32_e32 v46, v62, v57
	v_exp_f32_e32 v76, v47
	v_sub_f32_e32 v47, v50, v153
	v_add_f32_e32 v46, v74, v46
	v_exp_f32_e32 v77, v47
	v_sub_f32_e32 v47, v52, v153
	v_add_f32_e32 v46, v63, v46
	v_exp_f32_e32 v78, v47
	v_sub_f32_e32 v47, v51, v153
	v_add_f32_e32 v46, v75, v46
	v_exp_f32_e32 v79, v47
	v_sub_f32_e32 v22, v22, v153
	v_add_f32_e32 v46, v76, v46
	v_exp_f32_e32 v80, v22
	v_add_f32_e32 v46, v77, v46
	v_add_f32_e32 v46, v78, v46
	v_add_f32_e32 v46, v79, v46
	v_add_f32_e32 v22, v80, v46
	v_sub_f32_e32 v46, v53, v153
	v_exp_f32_e32 v81, v46
	v_sub_f32_e32 v46, v72, v153
	v_exp_f32_e32 v72, v46
	v_sub_f32_e32 v24, v24, v153
	v_exp_f32_e32 v82, v24
	v_sub_f32_e32 v23, v23, v153
	v_exp_f32_e32 v83, v23
	v_sub_f32_e32 v23, v25, v153
	v_add_f32_e32 v22, v81, v22
	v_exp_f32_e32 v84, v23
	v_sub_f32_e32 v23, v42, v153
	v_add_f32_e32 v22, v72, v22
	v_exp_f32_e32 v85, v23
	v_sub_f32_e32 v23, v43, v153
	v_add_f32_e32 v22, v82, v22
	v_exp_f32_e32 v86, v23
	v_sub_f32_e32 v0, v0, v153
	v_add_f32_e32 v22, v83, v22
	v_exp_f32_e32 v87, v0
	v_add_f32_e32 v22, v84, v22
	v_sub_f32_e32 v1, v1, v153
	v_add_f32_e32 v22, v85, v22
	v_exp_f32_e32 v101, v1
	v_sub_f32_e32 v1, v2, v153
	v_add_f32_e32 v22, v86, v22
	v_exp_f32_e32 v102, v1
	v_sub_f32_e32 v1, v3, v153
	s_or_b32 s20, s35, s60
	v_add_f32_e32 v0, v87, v22
	v_exp_f32_e32 v103, v1
	v_cvt_pk_bf16_f32 v22, v45, v64
	v_cvt_pk_bf16_f32 v23, v66, v65
	v_cvt_pk_bf16_f32 v24, v54, v55
	v_lshl_add_u32 v54, s20, 1, v121
	v_sub_f32_e32 v44, 0xf149f2ca, v153
	v_add_u32_e32 v50, v54, v123
	v_add_f32_e32 v0, v101, v0
	v_exp_f32_e32 v1, v44
	v_cvt_pk_bf16_f32 v25, v67, v56
	ds_read2_b64 v[42:45], v50 offset1:4
	v_add_u32_e32 v46, 0x4000, v50
	v_add_u32_e32 v50, 0x8000, v50
	v_add_u32_e32 v54, v54, v125
	v_add_f32_e32 v0, v102, v0
	ds_read2_b64 v[46:49], v46 offset0:32 offset1:36
	ds_read2_b64 v[50:53], v50 offset0:64 offset1:68
	ds_read2_b64 v[54:57], v54 offset1:4
	v_add_f32_e32 v0, v103, v0
	ds_bpermute_b32 v2, v145, v0
	s_or_b32 s20, s34, s60
	s_waitcnt lgkmcnt(0)
	v_add_f32_e32 v156, v0, v2
	v_mul_f32_e32 v0, 0, v1
	v_mov_b32_e32 v1, v0
	v_mov_b32_e32 v2, v0
	v_mov_b32_e32 v3, v0
	ds_bpermute_b32 v157, v149, v156
	s_nop 0
	v_mfma_f32_16x16x32_bf16 v[42:45], v[42:45], v[22:25], v[0:3]
	v_mfma_f32_16x16x32_bf16 v[46:49], v[46:49], v[22:25], v[0:3]
	v_mfma_f32_16x16x32_bf16 v[50:53], v[50:53], v[22:25], v[0:3]
	v_mfma_f32_16x16x32_bf16 v[22:25], v[54:57], v[22:25], v[0:3]
	v_cvt_pk_bf16_f32 v54, v73, v59
	v_cvt_pk_bf16_f32 v55, v60, v61
	v_cvt_pk_bf16_f32 v56, v62, v74
	v_cvt_pk_bf16_f32 v57, v63, v75
	s_nop 2
	v_lshl_add_u32 v1, s20, 1, v121
	v_add_u32_e32 v2, v1, v123
	ds_read2_b64 v[60:63], v2 offset1:4
	v_add_u32_e32 v3, 0x4000, v2
	s_waitcnt lgkmcnt(0)
	v_mfma_f32_16x16x32_bf16 v[42:45], v[60:63], v[54:57], v[42:45]
	ds_read2_b64 v[60:63], v3 offset0:32 offset1:36
	v_add_u32_e32 v2, 0x8000, v2
	v_add_u32_e32 v1, v1, v125
	s_waitcnt lgkmcnt(0)
	v_mfma_f32_16x16x32_bf16 v[46:49], v[60:63], v[54:57], v[46:49]
	ds_read2_b64 v[60:63], v2 offset0:64 offset1:68
	s_or_b32 s20, s33, s60
	s_waitcnt lgkmcnt(0)
	v_mfma_f32_16x16x32_bf16 v[50:53], v[60:63], v[54:57], v[50:53]
	ds_read2_b64 v[60:63], v1 offset1:4
	v_lshl_add_u32 v1, s20, 1, v121
	v_add_u32_e32 v2, v1, v123
	s_waitcnt lgkmcnt(0)
	v_mfma_f32_16x16x32_bf16 v[22:25], v[60:63], v[54:57], v[22:25]
	v_cvt_pk_bf16_f32 v54, v76, v77
	v_cvt_pk_bf16_f32 v55, v78, v79
	v_cvt_pk_bf16_f32 v56, v80, v81
	v_cvt_pk_bf16_f32 v57, v72, v82
	ds_read2_b64 v[60:63], v2 offset1:4
	v_add_u32_e32 v3, 0x4000, v2
	s_waitcnt lgkmcnt(0)
	v_mfma_f32_16x16x32_bf16 v[42:45], v[60:63], v[54:57], v[42:45]
	ds_read2_b64 v[60:63], v3 offset0:32 offset1:36
	v_add_u32_e32 v2, 0x8000, v2
	v_add_u32_e32 v1, v1, v125
	s_waitcnt lgkmcnt(0)
	v_mfma_f32_16x16x32_bf16 v[46:49], v[60:63], v[54:57], v[46:49]
	ds_read2_b64 v[60:63], v2 offset0:64 offset1:68
	s_or_b32 s20, s26, s60
	s_waitcnt lgkmcnt(0)
	v_mfma_f32_16x16x32_bf16 v[50:53], v[60:63], v[54:57], v[50:53]
	ds_read2_b64 v[60:63], v1 offset1:4
	v_lshl_add_u32 v1, s20, 1, v121
	v_add_u32_e32 v2, v1, v123
	s_waitcnt lgkmcnt(0)
	v_mfma_f32_16x16x32_bf16 v[22:25], v[60:63], v[54:57], v[22:25]
	v_cvt_pk_bf16_f32 v54, v83, v84
	v_cvt_pk_bf16_f32 v55, v85, v86
	v_cvt_pk_bf16_f32 v56, v87, v101
	v_cvt_pk_bf16_f32 v57, v102, v103
	ds_read2_b64 v[60:63], v2 offset1:4
	v_add_u32_e32 v3, 0x4000, v2
	s_waitcnt lgkmcnt(0)
	v_mfma_f32_16x16x32_bf16 v[42:45], v[60:63], v[54:57], v[42:45]
	ds_read2_b64 v[60:63], v3 offset0:32 offset1:36
	v_add_u32_e32 v2, 0x8000, v2
	v_add_u32_e32 v1, v1, v125
	s_waitcnt lgkmcnt(0)
	v_mfma_f32_16x16x32_bf16 v[46:49], v[60:63], v[54:57], v[46:49]
	ds_read2_b64 v[60:63], v2 offset0:64 offset1:68
	s_or_b32 s20, s22, 3
	s_waitcnt lgkmcnt(0)
	v_mfma_f32_16x16x32_bf16 v[50:53], v[60:63], v[54:57], v[50:53]
	ds_read2_b64 v[60:63], v1 offset1:4
	v_sub_u32_e64 v1, s20, 4 clamp
	s_waitcnt lgkmcnt(0)
	v_mfma_f32_16x16x32_bf16 v[54:57], v[60:63], v[54:57], v[22:25]
	v_readfirstlane_b32 s21, v1
	v_sub_u32_e64 v1, s20, 5 clamp
	s_min_u32 s21, s21, 8
	v_min_u32_e32 v1, 8, v1
	v_cmp_eq_u32_e32 vcc, s21, v1
	s_cbranch_vccnz .LBB0_124
	s_lshl_b32 s22, s21, 6
	s_addk_i32 s22, 0x1c0
	v_add_u32_e32 v2, s22, v108
	v_ashrrev_i32_e32 v3, 31, v2
	v_lshlrev_b64 v[2:3], 11, v[2:3]
	s_lshl_b32 s26, s21, 7
	v_lshl_add_u64 v[2:3], v[70:71], 0, v[2:3]
	v_lshl_add_u64 v[60:61], v[68:69], 0, s[26:27]
	s_barrier
	global_load_dwordx4 v[22:25], v[2:3], off
	s_nop 0
	global_load_dwordx4 v[60:63], v[60:61], off offset:896
	s_and_b32 s22, s22, 0x1c0
	v_add_u32_e32 v1, s22, v108
	v_mad_u64_u32 v[2:3], s[34:35], v1, s59, v[110:111]
	v_lshl_add_u32 v59, s22, 1, v109
	s_waitcnt vmcnt(1)
	ds_write_b128 v2, v[22:25]
	s_waitcnt vmcnt(0)
	ds_write_b128 v59, v[60:63]
	s_waitcnt lgkmcnt(0)
	s_barrier
.LBB0_124:
	v_lshl_or_b32 v1, s20, 6, v111
	v_or_b32_e32 v2, s2, v1
	v_mov_b32_e32 v3, s3
	v_lshlrev_b64 v[2:3], 11, v[2:3]
	v_lshl_add_u64 v[2:3], v[142:143], 0, v[2:3]
	global_load_dwordx4 v[22:25], v[2:3], off
	global_load_dwordx4 v[102:105], v[2:3], off offset:64
	s_add_i32 s21, s21, s61
	s_lshl_b32 s2, s21, 6
	s_and_b32 s33, s2, 0x1c0
	v_add_u32_e32 v1, s33, v115
	v_mad_u32_u24 v1, v1, s59, v117
	ds_read_b128 v[60:63], v1
	ds_read_b128 v[64:67], v1 offset:64
	v_add_u32_e32 v1, s33, v119
	v_mad_u32_u24 v1, v1, s59, v117
	s_sub_i32 s20, s21, s20
	s_add_i32 s21, s2, 64
	s_and_b32 s26, s21, 0x1c0
	s_add_i32 s21, s2, 0x80
	s_and_b32 s22, s21, 0x1c0
	s_addk_i32 s2, 0xc0
	s_and_b32 s2, s2, 0x1c0
	s_mul_i32 s20, s20, 31
	s_ashr_i32 s21, s20, 31
	s_lshl_b64 s[20:21], s[20:21], 2
	s_add_u32 s20, s36, s20
	s_addc_u32 s21, s23, s21
	v_readlane_b32 s0, v255, 10
	v_readlane_b32 s1, v255, 11
	s_waitcnt vmcnt(1) lgkmcnt(1)
	v_mfma_f32_16x16x32_bf16 v[60:63], v[60:63], v[22:25], 0
	s_waitcnt vmcnt(0) lgkmcnt(0)
	v_mfma_f32_16x16x32_bf16 v[84:87], v[64:67], v[102:105], v[60:63]
	s_nop 5
	ds_read_b128 v[60:63], v1
	ds_read_b128 v[64:67], v1 offset:64
	v_add_u32_e32 v1, s26, v115
	s_waitcnt lgkmcnt(1)
	v_mfma_f32_16x16x32_bf16 v[60:63], v[60:63], v[22:25], 0
	v_mad_u32_u24 v1, v1, s59, v117
	s_waitcnt lgkmcnt(0)
	v_mfma_f32_16x16x32_bf16 v[76:79], v[64:67], v[102:105], v[60:63]
	s_nop 4
	ds_read_b128 v[60:63], v1
	ds_read_b128 v[64:67], v1 offset:64
	v_add_u32_e32 v1, s26, v119
	v_mad_u32_u24 v1, v1, s59, v117
	s_waitcnt lgkmcnt(1)
	v_mfma_f32_16x16x32_bf16 v[60:63], v[60:63], v[22:25], 0
	s_waitcnt lgkmcnt(0)
	v_mfma_f32_16x16x32_bf16 v[80:83], v[64:67], v[102:105], v[60:63]
	s_nop 5
	ds_read_b128 v[60:63], v1
	ds_read_b128 v[64:67], v1 offset:64
	v_add_u32_e32 v1, s22, v115
	s_waitcnt lgkmcnt(1)
	v_mfma_f32_16x16x32_bf16 v[60:63], v[60:63], v[22:25], 0
	v_mad_u32_u24 v1, v1, s59, v117
	s_waitcnt lgkmcnt(0)
	v_mfma_f32_16x16x32_bf16 v[68:71], v[64:67], v[102:105], v[60:63]
	s_nop 4
	ds_read_b128 v[60:63], v1
	ds_read_b128 v[64:67], v1 offset:64
	v_add_u32_e32 v1, s22, v119
	v_mad_u32_u24 v1, v1, s59, v117
	s_waitcnt lgkmcnt(1)
	v_mfma_f32_16x16x32_bf16 v[60:63], v[60:63], v[22:25], 0
	s_waitcnt lgkmcnt(0)
	v_mfma_f32_16x16x32_bf16 v[72:75], v[64:67], v[102:105], v[60:63]
	s_nop 5
	ds_read_b128 v[60:63], v1
	ds_read_b128 v[64:67], v1 offset:64
	v_add_u32_e32 v1, s2, v115
	s_waitcnt lgkmcnt(1)
	v_mfma_f32_16x16x32_bf16 v[60:63], v[60:63], v[22:25], 0
	v_mad_u32_u24 v1, v1, s59, v117
	s_waitcnt lgkmcnt(0)
	v_mfma_f32_16x16x32_bf16 v[60:63], v[64:67], v[102:105], v[60:63]
	ds_read_b128 v[64:67], v1
	ds_read_b128 v[158:161], v1 offset:64
	v_add_u32_e32 v1, s2, v119
	v_mad_u32_u24 v1, v1, s59, v117
	s_waitcnt lgkmcnt(1)
	v_mfma_f32_16x16x32_bf16 v[64:67], v[64:67], v[22:25], 0
	s_or_b32 s2, s2, s60
	s_waitcnt lgkmcnt(0)
	v_mfma_f32_16x16x32_bf16 v[64:67], v[158:161], v[102:105], v[64:67]
	ds_read_b128 v[158:161], v1
	ds_read_b128 v[162:165], v1 offset:64
	global_load_dword v194, v99, s[20:21] offset:868
	global_load_dword v195, v98, s[20:21] offset:868
	global_load_dword v196, v96, s[20:21] offset:868
	global_load_dword v197, v97, s[20:21] offset:868
	global_load_dword v198, v93, s[20:21] offset:868
	global_load_dword v199, v94, s[20:21] offset:868
	global_load_dword v200, v95, s[20:21] offset:868
	global_load_dword v201, v92, s[20:21] offset:868
	global_load_dword v202, v99, s[20:21] offset:992
	global_load_dword v203, v96, s[20:21] offset:992
	global_load_dword v204, v98, s[20:21] offset:992
	global_load_dword v205, v94, s[20:21] offset:992
	global_load_dword v206, v97, s[20:21] offset:992
	global_load_dword v207, v93, s[20:21] offset:992
	global_load_dword v208, v95, s[20:21] offset:992
	global_load_dword v209, v92, s[20:21] offset:992
	global_load_dword v210, v99, s[20:21] offset:1116
	global_load_dword v211, v96, s[20:21] offset:1116
	global_load_dword v212, v98, s[20:21] offset:1116
	global_load_dword v213, v94, s[20:21] offset:1116
	global_load_dword v226, v97, s[20:21] offset:1116
	global_load_dword v227, v93, s[20:21] offset:1116
	global_load_dword v228, v95, s[20:21] offset:1116
	global_load_dword v229, v92, s[20:21] offset:1116
	global_load_dword v230, v99, s[20:21] offset:1240
	global_load_dword v231, v96, s[20:21] offset:1240
	global_load_dword v232, v98, s[20:21] offset:1240
	global_load_dword v233, v97, s[20:21] offset:1240
	global_load_dword v234, v93, s[20:21] offset:1240
	global_load_dword v235, v94, s[20:21] offset:1240
	global_load_dword v236, v95, s[20:21] offset:1240
	global_load_dword v237, v92, s[20:21] offset:1240
	s_waitcnt lgkmcnt(1)
	v_mfma_f32_16x16x32_bf16 v[22:25], v[158:161], v[22:25], 0
	s_waitcnt vmcnt(0)
	v_fmamk_f32 v1, v194, 0x3fb8aa3b, v84
	s_waitcnt lgkmcnt(0)
	v_mfma_f32_16x16x32_bf16 v[22:25], v[162:165], v[102:105], v[22:25]
	v_cndmask_b32_e64 v1, v220, v1, s[38:39]
	v_fmamk_f32 v76, v197, 0x3fb8aa3b, v76
	v_fmamk_f32 v3, v195, 0x3fb8aa3b, v86
	v_cndmask_b32_e64 v59, v220, v3, s[42:43]
	v_cndmask_b32_e64 v76, v220, v76, s[46:47]
	v_fmamk_f32 v77, v198, 0x3fb8aa3b, v77
	v_cndmask_b32_e64 v77, v220, v77, s[48:49]
	v_fmamk_f32 v78, v200, 0x3fb8aa3b, v78
	v_cndmask_b32_e64 v84, v220, v78, s[50:51]
	v_fmac_f32_e32 v87, 0x3fb8aa3b, v199
	v_cndmask_b32_e64 v3, v220, v87, s[44:45]
	v_fmac_f32_e32 v79, 0x3fb8aa3b, v201
	v_cndmask_b32_e64 v78, v220, v79, s[52:53]
	v_fmamk_f32 v79, v202, 0x3fb8aa3b, v80
	v_cndmask_b32_e64 v79, v220, v79, s[38:39]
	v_fmamk_f32 v80, v203, 0x3fb8aa3b, v81
	v_cndmask_b32_e64 v80, v220, v80, s[40:41]
	v_fmamk_f32 v81, v204, 0x3fb8aa3b, v82
	v_cndmask_b32_e64 v82, v220, v81, s[42:43]
	v_fmac_f32_e32 v83, 0x3fb8aa3b, v205
	v_cndmask_b32_e64 v81, v220, v83, s[44:45]
	v_fmamk_f32 v68, v206, 0x3fb8aa3b, v68
	v_cndmask_b32_e64 v68, v220, v68, s[46:47]
	v_fmamk_f32 v69, v207, 0x3fb8aa3b, v69
	v_cndmask_b32_e64 v69, v220, v69, s[48:49]
	v_fmamk_f32 v70, v208, 0x3fb8aa3b, v70
	v_cndmask_b32_e64 v83, v220, v70, s[50:51]
	v_fmamk_f32 v2, v196, 0x3fb8aa3b, v85
	v_cndmask_b32_e64 v2, v220, v2, s[40:41]
	v_fmac_f32_e32 v71, 0x3fb8aa3b, v209
	v_cndmask_b32_e64 v70, v220, v71, s[52:53]
	v_max_f32_e32 v86, v83, v70
	v_max3_f32 v86, v68, v69, v86
	v_fmamk_f32 v71, v210, 0x3fb8aa3b, v72
	v_cndmask_b32_e64 v71, v220, v71, s[38:39]
	v_fmamk_f32 v72, v211, 0x3fb8aa3b, v73
	v_cndmask_b32_e64 v72, v220, v72, s[40:41]
	v_fmamk_f32 v73, v212, 0x3fb8aa3b, v74
	v_cndmask_b32_e64 v74, v220, v73, s[42:43]
	v_fmac_f32_e32 v75, 0x3fb8aa3b, v213
	v_cndmask_b32_e64 v73, v220, v75, s[44:45]
	v_fmamk_f32 v60, v226, 0x3fb8aa3b, v60
	v_cndmask_b32_e64 v60, v220, v60, s[46:47]
	v_fmamk_f32 v61, v227, 0x3fb8aa3b, v61
	v_cndmask_b32_e64 v75, v220, v61, s[48:49]
	v_fmamk_f32 v61, v228, 0x3fb8aa3b, v62
	v_cndmask_b32_e64 v85, v220, v61, s[50:51]
	v_fmac_f32_e32 v63, 0x3fb8aa3b, v229
	v_cndmask_b32_e64 v62, v220, v63, s[52:53]
	v_fmamk_f32 v61, v230, 0x3fb8aa3b, v64
	v_cndmask_b32_e64 v61, v220, v61, s[38:39]
	v_fmamk_f32 v64, v232, 0x3fb8aa3b, v66
	v_cndmask_b32_e64 v64, v220, v64, s[42:43]
	v_fmamk_f32 v22, v233, 0x3fb8aa3b, v22
	v_fmamk_f32 v63, v231, 0x3fb8aa3b, v65
	v_cndmask_b32_e64 v63, v220, v63, s[40:41]
	v_cndmask_b32_e64 v22, v220, v22, s[46:47]
	v_fmamk_f32 v23, v234, 0x3fb8aa3b, v23
	v_cndmask_b32_e64 v23, v220, v23, s[48:49]
	v_fmamk_f32 v24, v236, 0x3fb8aa3b, v24
	v_fmac_f32_e32 v67, 0x3fb8aa3b, v235
	v_cndmask_b32_e64 v65, v220, v67, s[44:45]
	v_max_f32_e32 v67, v84, v78
	v_max3_f32 v67, v76, v77, v67
	s_mov_b32 s20, 0xf149f2ca
	v_cndmask_b32_e64 v24, v220, v24, s[50:51]
	v_fmac_f32_e32 v25, 0x3fb8aa3b, v237
	v_max_f32_e32 v66, v59, v3
	v_max3_f32 v66, v1, v2, v66
	v_max3_f32 v66, v66, s20, v67
	v_max_f32_e32 v67, v82, v81
	v_max3_f32 v67, v79, v80, v67
	v_max3_f32 v66, v66, v67, v86
	v_max_f32_e32 v67, v74, v73
	v_max_f32_e32 v86, v85, v62
	v_cndmask_b32_e64 v25, v220, v25, s[52:53]
	v_max3_f32 v67, v71, v72, v67
	v_max3_f32 v86, v60, v75, v86
	v_max3_f32 v66, v66, v67, v86
	v_max_f32_e32 v67, v64, v65
	v_max_f32_e32 v86, v24, v25
	v_max3_f32 v67, v61, v63, v67
	v_max3_f32 v86, v22, v23, v86
	v_max3_f32 v66, v66, v67, v86
	ds_bpermute_b32 v67, v145, v66
	s_waitcnt lgkmcnt(0)
	v_max_f32_e32 v67, v67, v67
	v_max_f32_e32 v66, v66, v67
	ds_bpermute_b32 v67, v149, v66
	s_waitcnt lgkmcnt(0)
	v_max3_f32 v159, v66, v67, s20
	v_sub_f32_e32 v1, v1, v159
	v_exp_f32_e32 v67, v1
	v_sub_f32_e32 v2, v2, v159
	v_exp_f32_e32 v2, v2
	v_sub_f32_e32 v59, v59, v159
	v_exp_f32_e32 v59, v59
	v_sub_f32_e32 v3, v3, v159
	v_exp_f32_e32 v3, v3
	v_sub_f32_e32 v76, v76, v159
	v_add_f32_e32 v1, 0, v67
	v_exp_f32_e32 v76, v76
	v_sub_f32_e32 v77, v77, v159
	v_add_f32_e32 v1, v2, v1
	v_exp_f32_e32 v77, v77
	v_sub_f32_e32 v84, v84, v159
	v_add_f32_e32 v1, v59, v1
	v_exp_f32_e32 v84, v84
	v_sub_f32_e32 v78, v78, v159
	v_add_f32_e32 v1, v3, v1
	v_exp_f32_e32 v78, v78
	v_sub_f32_e32 v79, v79, v159
	v_add_f32_e32 v1, v76, v1
	v_exp_f32_e32 v86, v79
	v_sub_f32_e32 v79, v80, v159
	v_add_f32_e32 v1, v77, v1
	v_exp_f32_e32 v80, v79
	v_sub_f32_e32 v79, v82, v159
	v_add_f32_e32 v1, v84, v1
	v_exp_f32_e32 v82, v79
	v_sub_f32_e32 v79, v81, v159
	v_add_f32_e32 v1, v78, v1
	v_exp_f32_e32 v81, v79
	v_sub_f32_e32 v68, v68, v159
	v_add_f32_e32 v1, v86, v1
	v_exp_f32_e32 v87, v68
	v_sub_f32_e32 v68, v69, v159
	v_add_f32_e32 v1, v80, v1
	v_exp_f32_e32 v92, v68
	v_sub_f32_e32 v68, v83, v159
	v_add_f32_e32 v1, v82, v1
	v_exp_f32_e32 v83, v68
	v_sub_f32_e32 v68, v70, v159
	v_add_f32_e32 v1, v81, v1
	v_exp_f32_e32 v93, v68
	v_sub_f32_e32 v68, v71, v159
	v_add_f32_e32 v1, v87, v1
	v_exp_f32_e32 v94, v68
	v_sub_f32_e32 v68, v72, v159
	v_add_f32_e32 v1, v92, v1
	v_exp_f32_e32 v95, v68
	v_sub_f32_e32 v68, v74, v159
	v_add_f32_e32 v1, v83, v1
	v_exp_f32_e32 v96, v68
	v_sub_f32_e32 v68, v73, v159
	v_add_f32_e32 v1, v93, v1
	v_exp_f32_e32 v97, v68
	v_sub_f32_e32 v60, v60, v159
	v_add_f32_e32 v1, v94, v1
	v_exp_f32_e32 v98, v60
	v_sub_f32_e32 v60, v75, v159
	v_add_f32_e32 v1, v95, v1
	v_exp_f32_e32 v99, v60
	v_sub_f32_e32 v60, v85, v159
	v_add_f32_e32 v1, v96, v1
	v_exp_f32_e32 v85, v60
	v_sub_f32_e32 v60, v62, v159
	v_add_f32_e32 v1, v97, v1
	v_exp_f32_e32 v101, v60
	v_sub_f32_e32 v60, v61, v159
	v_add_f32_e32 v1, v98, v1
	v_exp_f32_e32 v102, v60
	v_sub_f32_e32 v60, v63, v159
	v_add_f32_e32 v1, v99, v1
	v_exp_f32_e32 v103, v60
	v_sub_f32_e32 v60, v64, v159
	v_add_f32_e32 v1, v85, v1
	v_exp_f32_e32 v104, v60
	v_sub_f32_e32 v60, v65, v159
	v_add_f32_e32 v1, v101, v1
	v_exp_f32_e32 v105, v60
	v_sub_f32_e32 v22, v22, v159
	v_add_f32_e32 v1, v102, v1
	v_exp_f32_e32 v106, v22
	v_sub_f32_e32 v22, v23, v159
	v_add_f32_e32 v1, v103, v1
	v_exp_f32_e32 v107, v22
	v_sub_f32_e32 v22, v24, v159
	s_or_b32 s20, s33, s60
	v_add_f32_e32 v1, v104, v1
	v_exp_f32_e32 v147, v22
	v_sub_f32_e32 v22, v25, v159
	v_cvt_pk_bf16_f32 v60, v67, v2
	v_lshl_add_u32 v2, s20, 1, v121
	v_sub_f32_e32 v66, 0xf149f2ca, v159
	v_add_f32_e32 v1, v105, v1
	v_exp_f32_e32 v148, v22
	v_cvt_pk_bf16_f32 v61, v59, v3
	v_add_u32_e32 v3, v2, v123
	v_add_f32_e32 v1, v106, v1
	v_exp_f32_e32 v22, v66
	v_cvt_pk_bf16_f32 v62, v76, v77
	v_cvt_pk_bf16_f32 v63, v84, v78
	ds_read2_b64 v[64:67], v3 offset1:4
	v_add_u32_e32 v59, 0x4000, v3
	v_add_u32_e32 v3, 0x8000, v3
	v_add_u32_e32 v2, v2, v125
	v_add_f32_e32 v1, v107, v1
	ds_read2_b64 v[68:71], v59 offset0:32 offset1:36
	ds_read2_b64 v[72:75], v3 offset0:64 offset1:68
	ds_read2_b64 v[76:79], v2 offset1:4
	v_add_f32_e32 v1, v147, v1
	v_add_f32_e32 v1, v148, v1
	ds_bpermute_b32 v23, v145, v1
	s_or_b32 s20, s26, s60
	v_mul_f32_e32 v22, 0, v22
	v_lshl_add_u32 v2, s20, 1, v121
	v_mov_b32_e32 v24, v22
	s_waitcnt lgkmcnt(0)
	v_add_f32_e32 v1, v1, v23
	v_mov_b32_e32 v23, v22
	v_mov_b32_e32 v25, v22
	v_add_u32_e32 v3, v2, v123
	v_add_u32_e32 v2, v2, v125
	v_mfma_f32_16x16x32_bf16 v[64:67], v[64:67], v[60:63], v[22:25]
	s_or_b32 s20, s22, s60
	ds_bpermute_b32 v158, v149, v1
	v_mfma_f32_16x16x32_bf16 v[68:71], v[68:71], v[60:63], v[22:25]
	v_mfma_f32_16x16x32_bf16 v[72:75], v[72:75], v[60:63], v[22:25]
	v_mfma_f32_16x16x32_bf16 v[60:63], v[76:79], v[60:63], v[22:25]
	v_cvt_pk_bf16_f32 v76, v86, v80
	v_cvt_pk_bf16_f32 v77, v82, v81
	v_cvt_pk_bf16_f32 v78, v87, v92
	v_cvt_pk_bf16_f32 v79, v83, v93
	ds_read2_b64 v[80:83], v3 offset1:4
	s_nop 1
	v_add_u32_e32 v23, 0x4000, v3
	s_waitcnt lgkmcnt(0)
	v_mfma_f32_16x16x32_bf16 v[64:67], v[80:83], v[76:79], v[64:67]
	ds_read2_b64 v[80:83], v23 offset0:32 offset1:36
	v_add_u32_e32 v3, 0x8000, v3
	s_waitcnt lgkmcnt(0)
	v_mfma_f32_16x16x32_bf16 v[68:71], v[80:83], v[76:79], v[68:71]
	ds_read2_b64 v[80:83], v3 offset0:64 offset1:68
	s_waitcnt lgkmcnt(0)
	v_mfma_f32_16x16x32_bf16 v[72:75], v[80:83], v[76:79], v[72:75]
	ds_read2_b64 v[80:83], v2 offset1:4
	v_lshl_add_u32 v2, s20, 1, v121
	v_add_u32_e32 v3, v2, v123
	s_waitcnt lgkmcnt(0)
	v_mfma_f32_16x16x32_bf16 v[60:63], v[80:83], v[76:79], v[60:63]
	v_cvt_pk_bf16_f32 v76, v94, v95
	v_cvt_pk_bf16_f32 v77, v96, v97
	v_cvt_pk_bf16_f32 v78, v98, v99
	v_cvt_pk_bf16_f32 v79, v85, v101
	ds_read2_b64 v[80:83], v3 offset1:4
	v_add_u32_e32 v23, 0x4000, v3
	s_waitcnt lgkmcnt(0)
	v_mfma_f32_16x16x32_bf16 v[64:67], v[80:83], v[76:79], v[64:67]
	ds_read2_b64 v[80:83], v23 offset0:32 offset1:36
	v_add_u32_e32 v3, 0x8000, v3
	v_add_u32_e32 v2, v2, v125
	s_waitcnt lgkmcnt(0)
	v_mfma_f32_16x16x32_bf16 v[68:71], v[80:83], v[76:79], v[68:71]
	ds_read2_b64 v[80:83], v3 offset0:64 offset1:68
	s_waitcnt lgkmcnt(0)
	v_mfma_f32_16x16x32_bf16 v[72:75], v[80:83], v[76:79], v[72:75]
	ds_read2_b64 v[80:83], v2 offset1:4
	v_lshl_add_u32 v2, s2, 1, v121
	v_add_u32_e32 v3, v2, v123
	s_waitcnt lgkmcnt(0)
	v_mfma_f32_16x16x32_bf16 v[76:79], v[80:83], v[76:79], v[60:63]
	v_cvt_pk_bf16_f32 v80, v102, v103
	v_cvt_pk_bf16_f32 v81, v104, v105
	v_cvt_pk_bf16_f32 v82, v106, v107
	v_cvt_pk_bf16_f32 v83, v147, v148
	s_nop 2
	ds_read2_b64 v[60:63], v3 offset1:4
	v_add_u32_e32 v23, 0x4000, v3
	s_waitcnt lgkmcnt(0)
	v_mfma_f32_16x16x32_bf16 v[60:63], v[60:63], v[80:83], v[64:67]
	s_nop 2
	ds_read2_b64 v[64:67], v23 offset0:32 offset1:36
	v_add_u32_e32 v3, 0x8000, v3
	v_add_u32_e32 v2, v2, v125
	s_waitcnt lgkmcnt(0)
	v_mfma_f32_16x16x32_bf16 v[64:67], v[64:67], v[80:83], v[68:71]
	s_nop 2
	ds_read2_b64 v[68:71], v3 offset0:64 offset1:68
	s_waitcnt lgkmcnt(0)
	v_mfma_f32_16x16x32_bf16 v[68:71], v[68:71], v[80:83], v[72:75]
	s_nop 2
	ds_read2_b64 v[72:75], v2 offset1:4
	s_waitcnt lgkmcnt(0)
	v_mfma_f32_16x16x32_bf16 v[72:75], v[72:75], v[80:83], v[76:79]
	s_barrier
	s_and_saveexec_b64 s[20:21], s[0:1]
	s_xor_b64 s[20:21], exec, s[20:21]
	s_cbranch_execz .LBB0_130
	s_lshl_b64 s[22:23], s[56:57], 15
	v_lshl_add_u64 v[2:3], v[130:131], 0, s[22:23]
	s_movk_i32 s2, 0x90
	s_movk_i32 s26, 0x5ff
	v_mov_b32_e32 v23, v192
	v_ashrrev_i32_e32 v24, 3, v23
	v_ashrrev_i32_e32 v25, 31, v24
	v_lshlrev_b64 v[176:177], 7, v[24:25]
	v_lshl_add_u64 v[176:177], v[2:3], 0, v[176:177]
	global_load_dwordx4 v[76:79], v[176:177], off
	v_mad_u32_u24 v168, v24, s2, v110
	v_add_u32_e32 v23, 0x200, v192
	v_ashrrev_i32_e32 v24, 3, v23
	v_ashrrev_i32_e32 v25, 31, v24
	v_lshlrev_b64 v[176:177], 7, v[24:25]
	v_lshl_add_u64 v[176:177], v[2:3], 0, v[176:177]
	global_load_dwordx4 v[80:83], v[176:177], off
	v_mad_u32_u24 v169, v24, s2, v110
	v_add_u32_e32 v23, 0x400, v192
	v_ashrrev_i32_e32 v24, 3, v23
	v_ashrrev_i32_e32 v25, 31, v24
	v_lshlrev_b64 v[176:177], 7, v[24:25]
	v_lshl_add_u64 v[176:177], v[2:3], 0, v[176:177]
	global_load_dwordx4 v[84:87], v[176:177], off
	v_mad_u32_u24 v170, v24, s2, v110
	v_add_u32_e32 v23, 0x600, v192
	v_ashrrev_i32_e32 v24, 3, v23
	v_ashrrev_i32_e32 v25, 31, v24
	v_lshlrev_b64 v[176:177], 7, v[24:25]
	v_lshl_add_u64 v[176:177], v[2:3], 0, v[176:177]
	global_load_dwordx4 v[92:95], v[176:177], off
	v_mad_u32_u24 v171, v24, s2, v110
	v_lshl_add_u64 v[2:3], v[132:133], 0, s[22:23]
	s_movk_i32 s2, 0x210
	v_mov_b32_e32 v23, v192
	v_ashrrev_i32_e32 v24, 5, v23
	v_ashrrev_i32_e32 v25, 31, v24
	v_lshlrev_b64 v[176:177], 9, v[24:25]
	v_lshl_add_u64 v[176:177], v[2:3], 0, v[176:177]
	global_load_dwordx4 v[96:99], v[176:177], off
	v_mad_u32_u24 v172, v24, s2, v134
	v_add_u32_e32 v23, 0x200, v192
	v_ashrrev_i32_e32 v24, 5, v23
	v_ashrrev_i32_e32 v25, 31, v24
	v_lshlrev_b64 v[176:177], 9, v[24:25]
	v_lshl_add_u64 v[176:177], v[2:3], 0, v[176:177]
	global_load_dwordx4 v[104:107], v[176:177], off
	v_mad_u32_u24 v173, v24, s2, v134
	v_add_u32_e32 v23, 0x400, v192
	v_ashrrev_i32_e32 v24, 5, v23
	v_ashrrev_i32_e32 v25, 31, v24
	v_lshlrev_b64 v[176:177], 9, v[24:25]
	v_lshl_add_u64 v[176:177], v[2:3], 0, v[176:177]
	global_load_dwordx4 v[160:163], v[176:177], off
	v_mad_u32_u24 v174, v24, s2, v134
	v_add_u32_e32 v23, 0x600, v192
	v_ashrrev_i32_e32 v24, 5, v23
	v_ashrrev_i32_e32 v25, 31, v24
	v_lshlrev_b64 v[176:177], 9, v[24:25]
	v_lshl_add_u64 v[176:177], v[2:3], 0, v[176:177]
	global_load_dwordx4 v[164:167], v[176:177], off
	v_mad_u32_u24 v175, v24, s2, v134
	s_waitcnt vmcnt(7)
	ds_write_b128 v168, v[76:79]
	s_waitcnt vmcnt(6)
	ds_write_b128 v169, v[80:83]
	s_waitcnt vmcnt(5)
	ds_write_b128 v170, v[84:87]
	s_waitcnt vmcnt(4)
	ds_write_b128 v171, v[92:95]
	s_waitcnt vmcnt(3)
	ds_write_b128 v172, v[96:99]
	s_waitcnt vmcnt(2)
	ds_write_b128 v173, v[104:107]
	s_waitcnt vmcnt(1)
	ds_write_b128 v174, v[160:163]
	s_waitcnt vmcnt(0)
	ds_write_b128 v175, v[164:167]
